# plus gate and FFN-up epilogue operand loads issued before the leading half's alignment barrier
# speedup vs baseline: 1.0145x; 1.0030x over previous
; #define PG8_STAGE(bufoff, gbase, voff) do { _Pragma("unroll") for (int _i = 0; _i < 2; ++_i) \
;         __builtin_amdgcn_global_load_lds((const unsigned*)((const char*)(gbase) + (voff)[_i]), (PG8_LAS unsigned*)(lds + (bufoff) + ldsw + _i * 8192), 16, 0, 0); } while (0)
; #define PG8_LDA(dst, b, h) do { _Pragma("unroll") for (int m = 0; m < 4; ++m) _Pragma("unroll") for (int k = 0; k < 2; ++k) dst[m][k] = *(const PG8_LAS bf16x8*)(lds + PG8_SA(b, h) + aoff + m * 2048 + k * 1024); } while (0)
; #define PG8_LDB(dst, b, h) do { _Pragma("unroll") for (int n = 0; n < 2; ++n) _Pragma("unroll") for (int k = 0; k < 2; ++k) dst[n][k] = *(const PG8_LAS bf16x8*)(lds + PG8_SB(b, h) + boff + n * 2048 + k * 1024); } while (0)
; #define PG8_MMA(ai, bj, At, Bt) do { __builtin_amdgcn_s_setprio(1); _Pragma("unroll") for (int m = 0; m < 4; ++m) _Pragma("unroll") for (int n = 0; n < 2; ++n) _Pragma("unroll") for (int k = 0; k < 2; ++k) \
;         acc[ai][bj][m][n] = __builtin_amdgcn_mfma_f32_16x16x32_bf16(Bt[n][k], At[m][k], acc[ai][bj][m][n], 0, 0, 0); __builtin_amdgcn_s_setprio(0); } while (0)
; #define PG8_WAIT_V(n) asm volatile("s_waitcnt vmcnt(" #n ")" ::: "memory")
; #define PG8_WAIT_L(n) asm volatile("s_waitcnt lgkmcnt(" #n ")" ::: "memory")
; #define PG8_BAR __builtin_amdgcn_s_barrier()
; #define PG8_SCHED __builtin_amdgcn_sched_barrier(0)
; template <class Epi, class Sched, bool ALIGN_EPI = false, bool SP2 = false>
; __device__ __forceinline__ void gemm_phase(PG8_LAS unsigned char* lds, const Gemm g, const Sched& S, const Epi& E, const int tid) {
;     ...
;             PG8_LDB(B0, 0, 0); PG8_LDB(B1, 0, 1); PG8_SCHED; PG8_LDA(At, 0, 0); PG8_STAGE(PG8_SA(1, 1), a1 + hstep, voffA);
;             PG8_WAIT_V(8); PG8_WAIT_L(0); PG8_BAR; PG8_MMA(0, 0, At, B0); PG8_MMA(0, 1, At, B1); PG8_BAR; PG8_SCHED;
;             PG8_LDA(At, 0, 1); PG8_STAGE(PG8_SB(0, 0), b2, voffB); PG8_STAGE(PG8_SB(0, 1), b2 + hstep, voffB); PG8_STAGE(PG8_SA(0, 0), a2, voffA);
.LBB0_768:
	s_add_u32 s26, s24, 0xfff80080
	s_addc_u32 s27, s25, -1
	s_add_i32 s52, 0, 0x10000
	v_add_u32_e32 v68, s52, v157
	v_add_u32_e32 v154, s33, v157
	ds_read_b128 v[48:51], v68
	ds_read_b128 v[52:55], v68 offset:1024
	ds_read_b128 v[64:67], v68 offset:2048
	ds_read_b128 v[68:71], v68 offset:3072
	ds_read_b128 v[162:165], v154
	ds_read_b128 v[166:169], v154 offset:1024
	ds_read_b128 v[170:173], v154 offset:2048
	ds_read_b128 v[174:177], v154 offset:3072
	s_cmp_eq_u32 s51, 28
	s_cselect_b32 s29, s15, s27
	s_cselect_b32 s28, s21, s26
	s_cselect_b32 s27, s11, s50
	s_cselect_b32 s26, s48, s49
	v_lshl_add_u64 v[206:207], s[24:25], 0, v[150:151]
	s_add_i32 m0, s23, 0xc000
	ds_read_b128 v[178:181], v161
	ds_read_b128 v[182:185], v161 offset:1024
	ds_read_b128 v[186:189], v161 offset:2048
	ds_read_b128 v[190:193], v161 offset:3072
	ds_read_b128 v[194:197], v161 offset:4096
	ds_read_b128 v[198:201], v161 offset:5120
	ds_read_b128 v[202:205], v161 offset:6144
	ds_read_b128 v[214:217], v161 offset:7168
	global_load_lds_dwordx4 v[206:207], off
	v_lshl_add_u64 v[206:207], s[24:25], 0, v[152:153]
	s_add_i32 m0, s23, 0xe000
	s_nop 0
	global_load_lds_dwordx4 v[206:207], off
	s_waitcnt vmcnt(8)
	s_waitcnt lgkmcnt(0)
	s_barrier
	s_setprio 1
	s_waitcnt lgkmcnt(0)
	v_mfma_f32_16x16x32_bf16 v[140:143], v[48:51], v[178:181], v[140:143]
	v_mfma_f32_16x16x32_bf16 v[136:139], v[64:67], v[178:181], v[136:139]
	v_mfma_f32_16x16x32_bf16 v[124:127], v[48:51], v[186:189], v[124:127]
	v_mfma_f32_16x16x32_bf16 v[120:123], v[64:67], v[186:189], v[120:123]
	v_mfma_f32_16x16x32_bf16 v[108:111], v[48:51], v[194:197], v[108:111]
	v_mfma_f32_16x16x32_bf16 v[104:107], v[64:67], v[194:197], v[104:107]
	v_mfma_f32_16x16x32_bf16 v[92:95], v[48:51], v[202:205], v[92:95]
	v_mfma_f32_16x16x32_bf16 v[88:91], v[64:67], v[202:205], v[88:91]
	v_mfma_f32_16x16x32_bf16 v[140:143], v[52:55], v[182:185], v[140:143]
	v_mfma_f32_16x16x32_bf16 v[136:139], v[68:71], v[182:185], v[136:139]
	v_mfma_f32_16x16x32_bf16 v[124:127], v[52:55], v[190:193], v[124:127]
	v_mfma_f32_16x16x32_bf16 v[120:123], v[68:71], v[190:193], v[120:123]
	v_mfma_f32_16x16x32_bf16 v[108:111], v[52:55], v[198:201], v[108:111]
	v_mfma_f32_16x16x32_bf16 v[104:107], v[68:71], v[198:201], v[104:107]
	v_mfma_f32_16x16x32_bf16 v[92:95], v[52:55], v[214:217], v[92:95]
	v_mfma_f32_16x16x32_bf16 v[88:91], v[68:71], v[214:217], v[88:91]
	s_setprio 0
	s_setprio 1
	v_mfma_f32_16x16x32_bf16 v[132:135], v[162:165], v[178:181], v[132:135]
	v_mfma_f32_16x16x32_bf16 v[128:131], v[170:173], v[178:181], v[128:131]
	v_mfma_f32_16x16x32_bf16 v[116:119], v[162:165], v[186:189], v[116:119]
	v_mfma_f32_16x16x32_bf16 v[112:115], v[170:173], v[186:189], v[112:115]
	v_mfma_f32_16x16x32_bf16 v[100:103], v[162:165], v[194:197], v[100:103]
	v_mfma_f32_16x16x32_bf16 v[96:99], v[170:173], v[194:197], v[96:99]
	v_mfma_f32_16x16x32_bf16 v[84:87], v[162:165], v[202:205], v[84:87]
	v_mfma_f32_16x16x32_bf16 v[80:83], v[170:173], v[202:205], v[80:83]
	v_mfma_f32_16x16x32_bf16 v[132:135], v[166:169], v[182:185], v[132:135]
	v_mfma_f32_16x16x32_bf16 v[128:131], v[174:177], v[182:185], v[128:131]
	v_mfma_f32_16x16x32_bf16 v[116:119], v[166:169], v[190:193], v[116:119]
	v_mfma_f32_16x16x32_bf16 v[112:115], v[174:177], v[190:193], v[112:115]
	v_mfma_f32_16x16x32_bf16 v[100:103], v[166:169], v[198:201], v[100:103]
	v_mfma_f32_16x16x32_bf16 v[96:99], v[174:177], v[198:201], v[96:99]
	v_mfma_f32_16x16x32_bf16 v[84:87], v[166:169], v[214:217], v[84:87]
	v_mfma_f32_16x16x32_bf16 v[80:83], v[174:177], v[214:217], v[80:83]
	s_setprio 0
	s_barrier
	s_add_i32 s52, s52, s38
	v_lshl_add_u64 v[206:207], s[26:27], 0, v[208:209]
	s_mov_b32 m0, s52
	ds_read_b128 v[178:181], v161 offset:16384
	ds_read_b128 v[182:185], v161 offset:17408
	ds_read_b128 v[186:189], v161 offset:18432
	ds_read_b128 v[190:193], v161 offset:19456
	ds_read_b128 v[194:197], v161 offset:20480
	ds_read_b128 v[198:201], v161 offset:21504
	ds_read_b128 v[202:205], v161 offset:22528
	ds_read_b128 v[214:217], v161 offset:23552
	global_load_lds_dwordx4 v[206:207], off
	s_add_i32 m0, s52, 0x2000
	s_add_u32 s52, s26, 0x80000
	v_lshl_add_u64 v[210:211], s[26:27], 0, v[144:145]
	s_addc_u32 s53, s27, 0
	s_add_i32 s54, s33, s38
	global_load_lds_dwordx4 v[210:211], off
	v_lshl_add_u64 v[218:219], s[52:53], 0, v[208:209]
	s_mov_b32 m0, s54
	v_lshl_add_u64 v[220:221], s[28:29], 0, v[146:147]
	global_load_lds_dwordx4 v[218:219], off
	v_lshl_add_u64 v[218:219], s[52:53], 0, v[144:145]
	s_add_i32 m0, s54, 0x2000
	s_nop 0
	global_load_lds_dwordx4 v[218:219], off
	v_lshl_add_u64 v[218:219], s[28:29], 0, v[148:149]
	s_mov_b32 m0, s23
	s_nop 0
	global_load_lds_dwordx4 v[218:219], off
	s_mov_b32 m0, s39
	s_nop 0
	global_load_lds_dwordx4 v[220:221], off
	s_waitcnt vmcnt(8)
	s_waitcnt lgkmcnt(0)
	s_barrier
; #define PG8_STAGE(bufoff, gbase, voff) do { _Pragma("unroll") for (int _i = 0; _i < 2; ++_i) \
;         __builtin_amdgcn_global_load_lds((const unsigned*)((const char*)(gbase) + (voff)[_i]), (PG8_LAS unsigned*)(lds + (bufoff) + ldsw + _i * 8192), 16, 0, 0); } while (0)
; #define PG8_LDA(dst, b, h) do { _Pragma("unroll") for (int m = 0; m < 4; ++m) _Pragma("unroll") for (int k = 0; k < 2; ++k) dst[m][k] = *(const PG8_LAS bf16x8*)(lds + PG8_SA(b, h) + aoff + m * 2048 + k * 1024); } while (0)
; #define PG8_LDB(dst, b, h) do { _Pragma("unroll") for (int n = 0; n < 2; ++n) _Pragma("unroll") for (int k = 0; k < 2; ++k) dst[n][k] = *(const PG8_LAS bf16x8*)(lds + PG8_SB(b, h) + boff + n * 2048 + k * 1024); } while (0)
; #define PG8_MMA(ai, bj, At, Bt) do { __builtin_amdgcn_s_setprio(1); _Pragma("unroll") for (int m = 0; m < 4; ++m) _Pragma("unroll") for (int n = 0; n < 2; ++n) _Pragma("unroll") for (int k = 0; k < 2; ++k) \
;         acc[ai][bj][m][n] = __builtin_amdgcn_mfma_f32_16x16x32_bf16(Bt[n][k], At[m][k], acc[ai][bj][m][n], 0, 0, 0); __builtin_amdgcn_s_setprio(0); } while (0)
; #define PG8_WAIT_V(n) asm volatile("s_waitcnt vmcnt(" #n ")" ::: "memory")
; #define PG8_WAIT_L(n) asm volatile("s_waitcnt lgkmcnt(" #n ")" ::: "memory")
; #define PG8_BAR __builtin_amdgcn_s_barrier()
; #define PG8_SCHED __builtin_amdgcn_sched_barrier(0)
; template <class Epi, class Sched, bool ALIGN_EPI = false, bool SP2 = false>
; __device__ __forceinline__ void gemm_phase(PG8_LAS unsigned char* lds, const Gemm g, const Sched& S, const Epi& E, const int tid) {
;     ...
;             PG8_WAIT_V(8); PG8_WAIT_L(0); PG8_BAR; PG8_MMA(1, 0, At, B0); PG8_MMA(1, 1, At, B1); PG8_BAR; PG8_SCHED;
;             PG8_LDB(B0, 1, 0); PG8_LDB(B1, 1, 1); PG8_SCHED; PG8_LDA(At, 1, 0); PG8_STAGE(PG8_SA(0, 1), a2 + hstep, voffA);
;             PG8_WAIT_V(8); PG8_WAIT_L(0); PG8_BAR; PG8_MMA(0, 0, At, B0); PG8_MMA(0, 1, At, B1); PG8_BAR; PG8_SCHED;
	s_setprio 1
	s_waitcnt lgkmcnt(0)
	v_mfma_f32_16x16x32_bf16 v[76:79], v[48:51], v[178:181], v[76:79]
	v_mfma_f32_16x16x32_bf16 v[72:75], v[64:67], v[178:181], v[72:75]
	v_mfma_f32_16x16x32_bf16 v[44:47], v[48:51], v[186:189], v[44:47]
	v_mfma_f32_16x16x32_bf16 v[40:43], v[64:67], v[186:189], v[40:43]
	v_mfma_f32_16x16x32_bf16 v[28:31], v[48:51], v[194:197], v[28:31]
	v_mfma_f32_16x16x32_bf16 v[24:27], v[64:67], v[194:197], v[24:27]
	v_mfma_f32_16x16x32_bf16 v[12:15], v[48:51], v[202:205], v[12:15]
	v_mfma_f32_16x16x32_bf16 v[8:11], v[64:67], v[202:205], v[8:11]
	v_mfma_f32_16x16x32_bf16 v[76:79], v[52:55], v[182:185], v[76:79]
	v_mfma_f32_16x16x32_bf16 v[72:75], v[68:71], v[182:185], v[72:75]
	v_mfma_f32_16x16x32_bf16 v[44:47], v[52:55], v[190:193], v[44:47]
	v_mfma_f32_16x16x32_bf16 v[40:43], v[68:71], v[190:193], v[40:43]
	v_mfma_f32_16x16x32_bf16 v[28:31], v[52:55], v[198:201], v[28:31]
	v_mfma_f32_16x16x32_bf16 v[24:27], v[68:71], v[198:201], v[24:27]
	v_mfma_f32_16x16x32_bf16 v[12:15], v[52:55], v[214:217], v[12:15]
	v_mfma_f32_16x16x32_bf16 v[8:11], v[68:71], v[214:217], v[8:11]
	s_setprio 0
	s_setprio 1
	v_mfma_f32_16x16x32_bf16 v[36:39], v[162:165], v[186:189], v[36:39]
	v_mfma_f32_16x16x32_bf16 v[32:35], v[170:173], v[186:189], v[32:35]
	v_mfma_f32_16x16x32_bf16 v[20:23], v[162:165], v[194:197], v[20:23]
	v_mfma_f32_16x16x32_bf16 v[16:19], v[170:173], v[194:197], v[16:19]
	v_mfma_f32_16x16x32_bf16 v[4:7], v[162:165], v[202:205], v[4:7]
	v_mfma_f32_16x16x32_bf16 v[0:3], v[170:173], v[202:205], v[0:3]
	v_mfma_f32_16x16x32_bf16 v[48:51], v[162:165], v[178:181], v[60:63]
	v_mfma_f32_16x16x32_bf16 v[52:55], v[170:173], v[178:181], v[56:59]
	v_mfma_f32_16x16x32_bf16 v[36:39], v[166:169], v[190:193], v[36:39]
	v_mfma_f32_16x16x32_bf16 v[32:35], v[174:177], v[190:193], v[32:35]
	v_mfma_f32_16x16x32_bf16 v[20:23], v[166:169], v[198:201], v[20:23]
	v_mfma_f32_16x16x32_bf16 v[16:19], v[174:177], v[198:201], v[16:19]
	v_mfma_f32_16x16x32_bf16 v[4:7], v[166:169], v[214:217], v[4:7]
	v_mfma_f32_16x16x32_bf16 v[0:3], v[174:177], v[214:217], v[0:3]
	v_mfma_f32_16x16x32_bf16 v[48:51], v[166:169], v[182:185], v[48:51]
	v_mfma_f32_16x16x32_bf16 v[52:55], v[174:177], v[182:185], v[52:55]
	s_setprio 0
	s_barrier
	s_add_i32 s52, 0, 0x18000
	s_add_i32 s53, 0, 0x1c000
	v_add_u32_e32 v68, s52, v157
	v_add_u32_e32 v154, s53, v157
	ds_read_b128 v[56:59], v68
	ds_read_b128 v[60:63], v68 offset:1024
	ds_read_b128 v[64:67], v68 offset:2048
	ds_read_b128 v[68:71], v68 offset:3072
	ds_read_b128 v[162:165], v154
	ds_read_b128 v[166:169], v154 offset:1024
	ds_read_b128 v[170:173], v154 offset:2048
	ds_read_b128 v[174:177], v154 offset:3072
	s_add_u32 s28, s28, 0x80000
	s_addc_u32 s29, s29, 0
	s_mov_b32 m0, s40
	v_lshl_add_u64 v[222:223], s[28:29], 0, v[148:149]
	ds_read_b128 v[178:181], v161 offset:32768
	ds_read_b128 v[182:185], v161 offset:33792
	ds_read_b128 v[186:189], v161 offset:34816
	ds_read_b128 v[190:193], v161 offset:35840
	ds_read_b128 v[194:197], v161 offset:36864
	ds_read_b128 v[198:201], v161 offset:37888
	ds_read_b128 v[202:205], v161 offset:38912
	ds_read_b128 v[214:217], v161 offset:39936
	global_load_lds_dwordx4 v[222:223], off
	v_lshl_add_u64 v[222:223], s[28:29], 0, v[146:147]
	s_mov_b32 m0, s41
	s_nop 0
	global_load_lds_dwordx4 v[222:223], off
	s_waitcnt vmcnt(8)
	s_waitcnt lgkmcnt(0)
	s_barrier
	s_setprio 1
	s_waitcnt lgkmcnt(0)
	v_mfma_f32_16x16x32_bf16 v[140:143], v[56:59], v[178:181], v[140:143]
	v_mfma_f32_16x16x32_bf16 v[136:139], v[64:67], v[178:181], v[136:139]
	v_mfma_f32_16x16x32_bf16 v[124:127], v[56:59], v[186:189], v[124:127]
	v_mfma_f32_16x16x32_bf16 v[120:123], v[64:67], v[186:189], v[120:123]
	v_mfma_f32_16x16x32_bf16 v[108:111], v[56:59], v[194:197], v[108:111]
	v_mfma_f32_16x16x32_bf16 v[104:107], v[64:67], v[194:197], v[104:107]
	v_mfma_f32_16x16x32_bf16 v[92:95], v[56:59], v[202:205], v[92:95]
	v_mfma_f32_16x16x32_bf16 v[88:91], v[64:67], v[202:205], v[88:91]
	v_mfma_f32_16x16x32_bf16 v[140:143], v[60:63], v[182:185], v[140:143]
	v_mfma_f32_16x16x32_bf16 v[136:139], v[68:71], v[182:185], v[136:139]
	v_mfma_f32_16x16x32_bf16 v[124:127], v[60:63], v[190:193], v[124:127]
	v_mfma_f32_16x16x32_bf16 v[120:123], v[68:71], v[190:193], v[120:123]
	v_mfma_f32_16x16x32_bf16 v[108:111], v[60:63], v[198:201], v[108:111]
	v_mfma_f32_16x16x32_bf16 v[104:107], v[68:71], v[198:201], v[104:107]
	v_mfma_f32_16x16x32_bf16 v[92:95], v[60:63], v[214:217], v[92:95]
	v_mfma_f32_16x16x32_bf16 v[88:91], v[68:71], v[214:217], v[88:91]
	s_setprio 0
	s_setprio 1
	v_mfma_f32_16x16x32_bf16 v[132:135], v[162:165], v[178:181], v[132:135]
	v_mfma_f32_16x16x32_bf16 v[128:131], v[170:173], v[178:181], v[128:131]
	v_mfma_f32_16x16x32_bf16 v[116:119], v[162:165], v[186:189], v[116:119]
	v_mfma_f32_16x16x32_bf16 v[112:115], v[170:173], v[186:189], v[112:115]
	v_mfma_f32_16x16x32_bf16 v[100:103], v[162:165], v[194:197], v[100:103]
	v_mfma_f32_16x16x32_bf16 v[96:99], v[170:173], v[194:197], v[96:99]
	v_mfma_f32_16x16x32_bf16 v[84:87], v[162:165], v[202:205], v[84:87]
	v_mfma_f32_16x16x32_bf16 v[80:83], v[170:173], v[202:205], v[80:83]
	v_mfma_f32_16x16x32_bf16 v[132:135], v[166:169], v[182:185], v[132:135]
	v_mfma_f32_16x16x32_bf16 v[128:131], v[174:177], v[182:185], v[128:131]
	v_mfma_f32_16x16x32_bf16 v[116:119], v[166:169], v[190:193], v[116:119]
	v_mfma_f32_16x16x32_bf16 v[112:115], v[174:177], v[190:193], v[112:115]
	v_mfma_f32_16x16x32_bf16 v[100:103], v[166:169], v[198:201], v[100:103]
	v_mfma_f32_16x16x32_bf16 v[96:99], v[174:177], v[198:201], v[96:99]
	v_mfma_f32_16x16x32_bf16 v[84:87], v[166:169], v[214:217], v[84:87]
	v_mfma_f32_16x16x32_bf16 v[80:83], v[174:177], v[214:217], v[80:83]
	s_setprio 0
	s_barrier
; #define PG8_STAGE(bufoff, gbase, voff) do { _Pragma("unroll") for (int _i = 0; _i < 2; ++_i) \
;         __builtin_amdgcn_global_load_lds((const unsigned*)((const char*)(gbase) + (voff)[_i]), (PG8_LAS unsigned*)(lds + (bufoff) + ldsw + _i * 8192), 16, 0, 0); } while (0)
; #define PG8_LDA(dst, b, h) do { _Pragma("unroll") for (int m = 0; m < 4; ++m) _Pragma("unroll") for (int k = 0; k < 2; ++k) dst[m][k] = *(const PG8_LAS bf16x8*)(lds + PG8_SA(b, h) + aoff + m * 2048 + k * 1024); } while (0)
; #define PG8_MMA(ai, bj, At, Bt) do { __builtin_amdgcn_s_setprio(1); _Pragma("unroll") for (int m = 0; m < 4; ++m) _Pragma("unroll") for (int n = 0; n < 2; ++n) _Pragma("unroll") for (int k = 0; k < 2; ++k) \
;         acc[ai][bj][m][n] = __builtin_amdgcn_mfma_f32_16x16x32_bf16(Bt[n][k], At[m][k], acc[ai][bj][m][n], 0, 0, 0); __builtin_amdgcn_s_setprio(0); } while (0)
; #define PG8_WAIT_V(n) asm volatile("s_waitcnt vmcnt(" #n ")" ::: "memory")
; #define PG8_WAIT_L(n) asm volatile("s_waitcnt lgkmcnt(" #n ")" ::: "memory")
; #define PG8_BAR __builtin_amdgcn_s_barrier()
; #define PG8_SCHED __builtin_amdgcn_sched_barrier(0)
; template <class Epi, class Sched, bool ALIGN_EPI = false, bool SP2 = false>
; __device__ __forceinline__ void gemm_phase(PG8_LAS unsigned char* lds, const Gemm g, const Sched& S, const Epi& E, const int tid) {
;     ...
;             PG8_LDA(At, 1, 1); PG8_STAGE(PG8_SB(1, 0), b3, voffB); PG8_STAGE(PG8_SB(1, 1), b3 + hstep, voffB); PG8_STAGE(PG8_SA(1, 0), a3, voffA);
;             PG8_WAIT_V(8); PG8_WAIT_L(0); PG8_BAR; PG8_MMA(1, 0, At, B0); PG8_MMA(1, 1, At, B1); PG8_BAR; PG8_SCHED;
;     __device__ __forceinline__ void operator()(const f32x4 (&acc)[2][2][4][2], const Unit& un, int wr, int wc, int fr, int fq) const {
;         const int rbase = un.pm * 256 + wr * 64 + fr, cw = un.pn * 256 + wc * 32 + 8 * fq;
;         const int slot = un.pm < (NLAT / 256) ? (un.pm >> 5) : 4; const float* sw = shw + (size_t)slot * DFF;
;         f32x4 s0[2], s1[2]; float rr[2][4];
; #pragma unroll
;         for (int bj = 0; bj < 2; ++bj) { s0[bj] = *(const f32x4*)(sw + cw + bj * 128); s1[bj] = *(const f32x4*)(sw + cw + bj * 128 + 4); }
; #pragma unroll
;         for (int ai = 0; ai < 2; ++ai)
; #pragma unroll
;             for (int m = 0; m < 4; ++m) rr[ai][m] = rs[rbase + ai * 128 + m * 16];
	s_add_i32 s28, s52, s38
	v_lshl_add_u64 v[206:207], v[206:207], 0, s[2:3]
	s_mov_b32 m0, s28
	ds_read_b128 v[178:181], v161 offset:49152
	ds_read_b128 v[182:185], v161 offset:50176
	ds_read_b128 v[186:189], v161 offset:51200
	ds_read_b128 v[190:193], v161 offset:52224
	ds_read_b128 v[194:197], v161 offset:53248
	ds_read_b128 v[198:201], v161 offset:54272
	ds_read_b128 v[202:205], v161 offset:55296
	ds_read_b128 v[214:217], v161 offset:56320
	global_load_lds_dwordx4 v[206:207], off
	s_add_i32 m0, s28, 0x2000
	s_add_u32 s26, s26, 0x80080
	v_lshl_add_u64 v[206:207], v[210:211], 0, s[2:3]
	s_addc_u32 s27, s27, 0
	s_add_i32 s28, s53, s38
	global_load_lds_dwordx4 v[206:207], off
	v_lshl_add_u64 v[206:207], s[26:27], 0, v[208:209]
	s_mov_b32 m0, s28
	s_nop 0
	global_load_lds_dwordx4 v[206:207], off
	v_lshl_add_u64 v[206:207], s[26:27], 0, v[144:145]
	s_add_i32 m0, s28, 0x2000
	s_nop 0
	global_load_lds_dwordx4 v[206:207], off
	v_lshl_add_u64 v[206:207], v[218:219], 0, s[2:3]
	s_mov_b32 m0, s45
	s_nop 0
	global_load_lds_dwordx4 v[206:207], off
	v_lshl_add_u64 v[206:207], v[220:221], 0, s[2:3]
	s_mov_b32 m0, s46
	s_nop 0
	global_load_lds_dwordx4 v[206:207], off
	s_waitcnt vmcnt(8)
	s_waitcnt lgkmcnt(0)
	s_barrier
	s_setprio 1
	s_waitcnt lgkmcnt(0)
	v_mfma_f32_16x16x32_bf16 v[76:79], v[56:59], v[178:181], v[76:79]
	v_mfma_f32_16x16x32_bf16 v[72:75], v[64:67], v[178:181], v[72:75]
	v_mfma_f32_16x16x32_bf16 v[44:47], v[56:59], v[186:189], v[44:47]
	v_mfma_f32_16x16x32_bf16 v[40:43], v[64:67], v[186:189], v[40:43]
	v_mfma_f32_16x16x32_bf16 v[28:31], v[56:59], v[194:197], v[28:31]
	v_mfma_f32_16x16x32_bf16 v[24:27], v[64:67], v[194:197], v[24:27]
	v_mfma_f32_16x16x32_bf16 v[12:15], v[56:59], v[202:205], v[12:15]
	v_mfma_f32_16x16x32_bf16 v[8:11], v[64:67], v[202:205], v[8:11]
	v_mfma_f32_16x16x32_bf16 v[76:79], v[60:63], v[182:185], v[76:79]
	v_mfma_f32_16x16x32_bf16 v[72:75], v[68:71], v[182:185], v[72:75]
	v_mfma_f32_16x16x32_bf16 v[44:47], v[60:63], v[190:193], v[44:47]
	v_mfma_f32_16x16x32_bf16 v[40:43], v[68:71], v[190:193], v[40:43]
	v_mfma_f32_16x16x32_bf16 v[28:31], v[60:63], v[198:201], v[28:31]
	v_mfma_f32_16x16x32_bf16 v[24:27], v[68:71], v[198:201], v[24:27]
	v_mfma_f32_16x16x32_bf16 v[12:15], v[60:63], v[214:217], v[12:15]
	v_mfma_f32_16x16x32_bf16 v[8:11], v[68:71], v[214:217], v[8:11]
	s_setprio 0
	s_setprio 1
	v_mfma_f32_16x16x32_bf16 v[48:51], v[162:165], v[178:181], v[48:51]
	v_mfma_f32_16x16x32_bf16 v[60:63], v[166:169], v[182:185], v[48:51]
	v_mfma_f32_16x16x32_bf16 v[48:51], v[170:173], v[178:181], v[52:55]
	v_mfma_f32_16x16x32_bf16 v[36:39], v[162:165], v[186:189], v[36:39]
	v_mfma_f32_16x16x32_bf16 v[32:35], v[170:173], v[186:189], v[32:35]
	v_mfma_f32_16x16x32_bf16 v[20:23], v[162:165], v[194:197], v[20:23]
	v_mfma_f32_16x16x32_bf16 v[16:19], v[170:173], v[194:197], v[16:19]
	v_mfma_f32_16x16x32_bf16 v[4:7], v[162:165], v[202:205], v[4:7]
	v_mfma_f32_16x16x32_bf16 v[0:3], v[170:173], v[202:205], v[0:3]
	v_mfma_f32_16x16x32_bf16 v[56:59], v[174:177], v[182:185], v[48:51]
	v_mfma_f32_16x16x32_bf16 v[36:39], v[166:169], v[190:193], v[36:39]
	v_mfma_f32_16x16x32_bf16 v[32:35], v[174:177], v[190:193], v[32:35]
	v_mfma_f32_16x16x32_bf16 v[20:23], v[166:169], v[198:201], v[20:23]
	v_mfma_f32_16x16x32_bf16 v[16:19], v[174:177], v[198:201], v[16:19]
	v_mfma_f32_16x16x32_bf16 v[4:7], v[166:169], v[214:217], v[4:7]
	v_mfma_f32_16x16x32_bf16 v[0:3], v[174:177], v[214:217], v[0:3]
	s_setprio 0
	s_barrier
	s_add_i32 s51, s51, 2
	s_add_u32 s24, s24, 0x100
	s_addc_u32 s25, s25, 0
	s_add_u32 s49, s49, 0x100
	s_addc_u32 s50, s50, 0
	s_cmp_gt_u32 s51, 29
	s_cbranch_scc0 .LBB0_768
	s_ashr_i32 s24, s20, 5
	s_ashr_i32 s25, s24, 31
	s_lshl_b64 s[24:25], s[24:25], 13
	s_cmpk_lt_i32 s20, 0x80
	s_cselect_b32 s25, s25, 0
	s_cselect_b32 s24, s24, 0x8000
	s_lshl_b64 s[24:25], s[24:25], 2
	v_lshl_or_b32 v176, s22, 8, v159
	s_add_u32 s24, s42, s24
	v_lshl_add_u32 v178, s20, 8, v155
	s_addc_u32 s25, s43, s25
	v_ashrrev_i32_e32 v177, 31, v176
	v_ashrrev_i32_e32 v179, 31, v178
	v_lshl_add_u64 v[52:53], v[176:177], 2, s[24:25]
	v_lshl_add_u64 v[180:181], v[178:179], 2, s[6:7]
	global_load_dwordx4 v[64:67], v[52:53], off offset:16
	global_load_dwordx4 v[68:71], v[52:53], off
	global_load_dwordx4 v[48:51], v[52:53], off offset:528
	s_nop 0
	global_load_dwordx4 v[52:55], v[52:53], off offset:512
	v_or_b32_e32 v172, 16, v178
	global_load_dword v174, v[180:181], off
	v_ashrrev_i32_e32 v173, 31, v172
	v_lshl_add_u64 v[162:163], v[172:173], 2, s[6:7]
	global_load_dword v170, v[162:163], off
	v_or_b32_e32 v168, 32, v178
	v_ashrrev_i32_e32 v169, 31, v168
	v_lshl_add_u64 v[162:163], v[168:169], 2, s[6:7]
	global_load_dword v166, v[162:163], off
	v_or_b32_e32 v164, 48, v178
	v_lshlrev_b64 v[178:179], 14, v[178:179]
	v_ashrrev_i32_e32 v165, 31, v164
	v_lshl_add_u64 v[162:163], v[164:165], 2, s[6:7]
	global_load_dword v162, v[162:163], off
	s_nop 0
	global_load_dword v160, v[180:181], off offset:512
	global_load_dword v158, v[180:181], off offset:576
	global_load_dword v156, v[180:181], off offset:640
	global_load_dword v154, v[180:181], off offset:704
	s_and_b64 vcc, exec, s[8:9]
	s_cbranch_vccz .LBB0_771
	s_barrier
; __device__ __forceinline__ unsigned pk2(float lo, float hi) { const f32x2 v = {lo, hi}; return __builtin_bit_cast(unsigned, __builtin_convertvector(v, bf16x2_t)); }
; __device__ __forceinline__ float sigmoidf_(float x) { return __builtin_amdgcn_rcpf(1.f + __builtin_amdgcn_exp2f(-x * LOG2E)); }
; #define EPI_LOOP _Pragma("unroll") for (int ai = 0; ai < 2; ++ai) _Pragma("unroll") for (int m = 0; m < 4; ++m) _Pragma("unroll") for (int bj = 0; bj < 2; ++bj)
;     __device__ __forceinline__ void operator()(const f32x4 (&acc)[2][2][4][2], const Unit& un, int wr, int wc, int fr, int fq) const {
;     ...
;         EPI_LOOP { const int row = rbase + ai * 128 + m * 16, col = cw + bj * 128; const float r = rr[ai][m];
;             f32x4 v0 = acc[ai][bj][m][0] * r + s0[bj], v1 = acc[ai][bj][m][1] * r + s1[bj];
;             v0 = (f32x4){sigmoidf_(v0.x), sigmoidf_(v0.y), sigmoidf_(v0.z), sigmoidf_(v0.w)}; v1 = (f32x4){sigmoidf_(v1.x), sigmoidf_(v1.y), sigmoidf_(v1.z), sigmoidf_(v1.w)};
;             u32x4 w; w.x = pk2(v0.x, v0.y); w.y = pk2(v0.z, v0.w); w.z = pk2(v1.x, v1.y); w.w = pk2(v1.z, v1.w);
;             *(u32x4*)(o + (size_t)row * DFF + col) = w; }
.LBB0_771:
	s_mov_b64 s[20:21], 0x240000
	s_waitcnt vmcnt(0)
	v_pk_fma_f32 v[142:143], v[142:143], v[174:175], v[70:71] op_sel_hi:[1,0,1]
	v_pk_fma_f32 v[140:141], v[140:141], v[174:175], v[68:69] op_sel_hi:[1,0,1]
	v_pk_fma_f32 v[138:139], v[138:139], v[174:175], v[66:67] op_sel_hi:[1,0,1]
	v_pk_fma_f32 v[136:137], v[136:137], v[174:175], v[64:65] op_sel_hi:[1,0,1]
	v_mul_f32_e32 v140, 0xbfb8aa3b, v140
	v_mul_f32_e32 v141, 0xbfb8aa3b, v141
	v_mul_f32_e32 v142, 0xbfb8aa3b, v142
	v_mul_f32_e32 v143, 0xbfb8aa3b, v143
	v_mul_f32_e32 v136, 0xbfb8aa3b, v136
	v_mul_f32_e32 v137, 0xbfb8aa3b, v137
	v_mul_f32_e32 v138, 0xbfb8aa3b, v138
	v_mul_f32_e32 v139, 0xbfb8aa3b, v139
	v_exp_f32_e32 v140, v140
	v_exp_f32_e32 v141, v141
	v_exp_f32_e32 v142, v142
	v_exp_f32_e32 v143, v143
	v_exp_f32_e32 v136, v136
	v_exp_f32_e32 v137, v137
	v_exp_f32_e32 v138, v138
	v_exp_f32_e32 v139, v139
	v_add_f32_e32 v140, 1.0, v140
	v_add_f32_e32 v141, 1.0, v141
	v_add_f32_e32 v142, 1.0, v142
	v_add_f32_e32 v143, 1.0, v143
	v_add_f32_e32 v136, 1.0, v136
	v_add_f32_e32 v137, 1.0, v137
	v_add_f32_e32 v138, 1.0, v138
	v_add_f32_e32 v139, 1.0, v139
	v_pk_fma_f32 v[128:129], v[128:129], v[174:175], v[48:49] op_sel_hi:[1,0,1]
	v_rcp_f32_e32 v140, v140
	v_rcp_f32_e32 v141, v141
	v_rcp_f32_e32 v142, v142
	v_rcp_f32_e32 v143, v143
	v_rcp_f32_e32 v136, v136
	v_rcp_f32_e32 v137, v137
	v_rcp_f32_e32 v138, v138
	v_rcp_f32_e32 v139, v139
	v_mul_f32_e32 v128, 0xbfb8aa3b, v128
	v_exp_f32_e32 v128, v128
	v_cvt_pk_bf16_f32 v140, v140, v141
	v_cvt_pk_bf16_f32 v141, v142, v143
	v_cvt_pk_bf16_f32 v142, v136, v137
	v_cvt_pk_bf16_f32 v143, v138, v139
	v_lshl_add_u64 v[136:137], s[4:5], 0, v[178:179]
	v_lshlrev_b64 v[138:139], 1, v[176:177]
	v_lshl_add_u64 v[136:137], v[136:137], 0, v[138:139]
	v_add_f32_e32 v128, 1.0, v128
	global_store_dwordx4 v[136:137], v[140:143], off
	v_pk_fma_f32 v[130:131], v[130:131], v[174:175], v[50:51] op_sel_hi:[1,0,1]
	v_pk_fma_f32 v[134:135], v[134:135], v[174:175], v[54:55] op_sel_hi:[1,0,1]
	v_rcp_f32_e32 v140, v128
	v_mul_f32_e32 v128, 0xbfb8aa3b, v129
	v_exp_f32_e32 v128, v128
	v_pk_fma_f32 v[132:133], v[132:133], v[174:175], v[52:53] op_sel_hi:[1,0,1]
	v_mul_f32_e32 v134, 0xbfb8aa3b, v134
	v_mul_f32_e32 v132, 0xbfb8aa3b, v132
	v_add_f32_e32 v128, 1.0, v128
	v_rcp_f32_e32 v141, v128
	v_mul_f32_e32 v128, 0xbfb8aa3b, v130
	v_exp_f32_e32 v128, v128
	v_mul_f32_e32 v133, 0xbfb8aa3b, v133
	v_mul_f32_e32 v135, 0xbfb8aa3b, v135
	v_exp_f32_e32 v132, v132
	v_add_f32_e32 v128, 1.0, v128
	v_rcp_f32_e32 v142, v128
	v_mul_f32_e32 v128, 0xbfb8aa3b, v131
	v_exp_f32_e32 v133, v133
	v_exp_f32_e32 v134, v134
	v_exp_f32_e32 v135, v135
	v_exp_f32_e32 v128, v128
	v_pk_fma_f32 v[120:121], v[120:121], v[170:171], v[64:65] op_sel_hi:[1,0,1]
	v_add_f32_e32 v132, 1.0, v132
	v_add_f32_e32 v133, 1.0, v133
	v_add_f32_e32 v134, 1.0, v134
	v_add_f32_e32 v135, 1.0, v135
	v_add_f32_e32 v128, 1.0, v128
	v_mul_f32_e32 v120, 0xbfb8aa3b, v120
	v_rcp_f32_e32 v132, v132
	v_rcp_f32_e32 v133, v133
	v_rcp_f32_e32 v134, v134
	v_rcp_f32_e32 v135, v135
	v_rcp_f32_e32 v131, v128
	v_exp_f32_e32 v120, v120
	v_cvt_pk_bf16_f32 v128, v132, v133
	v_cvt_pk_bf16_f32 v129, v134, v135
	v_cvt_pk_bf16_f32 v130, v140, v141
	v_cvt_pk_bf16_f32 v131, v142, v131
	v_add_f32_e32 v120, 1.0, v120
	global_store_dwordx4 v[136:137], v[128:131], off offset:256
	v_pk_fma_f32 v[122:123], v[122:123], v[170:171], v[66:67] op_sel_hi:[1,0,1]
	v_pk_fma_f32 v[124:125], v[124:125], v[170:171], v[68:69] op_sel_hi:[1,0,1]
	v_rcp_f32_e32 v130, v120
	v_mul_f32_e32 v120, 0xbfb8aa3b, v121
	v_exp_f32_e32 v120, v120
	v_pk_fma_f32 v[126:127], v[126:127], v[170:171], v[70:71] op_sel_hi:[1,0,1]
	v_mul_f32_e32 v124, 0xbfb8aa3b, v124
	v_mul_f32_e32 v125, 0xbfb8aa3b, v125
	v_add_f32_e32 v120, 1.0, v120
	v_rcp_f32_e32 v131, v120
	v_mul_f32_e32 v120, 0xbfb8aa3b, v122
	v_exp_f32_e32 v120, v120
	v_exp_f32_e32 v124, v124
	v_exp_f32_e32 v125, v125
	v_mul_f32_e32 v126, 0xbfb8aa3b, v126
	v_add_f32_e32 v120, 1.0, v120
	v_mul_f32_e32 v127, 0xbfb8aa3b, v127
	v_rcp_f32_e32 v132, v120
	v_mul_f32_e32 v120, 0xbfb8aa3b, v123
	v_exp_f32_e32 v126, v126
	v_exp_f32_e32 v127, v127
	v_exp_f32_e32 v120, v120
	v_add_f32_e32 v124, 1.0, v124
	v_add_f32_e32 v125, 1.0, v125
	v_pk_fma_f32 v[112:113], v[112:113], v[170:171], v[48:49] op_sel_hi:[1,0,1]
	v_rcp_f32_e32 v124, v124
	v_rcp_f32_e32 v125, v125
	v_add_f32_e32 v126, 1.0, v126
	v_add_f32_e32 v127, 1.0, v127
	v_add_f32_e32 v120, 1.0, v120
	v_mul_f32_e32 v112, 0xbfb8aa3b, v112
	v_rcp_f32_e32 v126, v126
	v_rcp_f32_e32 v127, v127
	v_rcp_f32_e32 v123, v120
	v_exp_f32_e32 v112, v112
	v_lshlrev_b64 v[128:129], 14, v[172:173]
	v_cvt_pk_bf16_f32 v120, v124, v125
	v_lshl_add_u64 v[124:125], s[4:5], 0, v[128:129]
	v_cvt_pk_bf16_f32 v121, v126, v127
	v_cvt_pk_bf16_f32 v122, v130, v131
	v_cvt_pk_bf16_f32 v123, v132, v123
	v_lshl_add_u64 v[124:125], v[124:125], 0, v[138:139]
	v_add_f32_e32 v112, 1.0, v112
	global_store_dwordx4 v[124:125], v[120:123], off
	v_pk_fma_f32 v[114:115], v[114:115], v[170:171], v[50:51] op_sel_hi:[1,0,1]
	v_pk_fma_f32 v[118:119], v[118:119], v[170:171], v[54:55] op_sel_hi:[1,0,1]
	v_rcp_f32_e32 v120, v112
	v_mul_f32_e32 v112, 0xbfb8aa3b, v113
	v_exp_f32_e32 v112, v112
	v_pk_fma_f32 v[116:117], v[116:117], v[170:171], v[52:53] op_sel_hi:[1,0,1]
	v_mul_f32_e32 v118, 0xbfb8aa3b, v118
	v_mul_f32_e32 v116, 0xbfb8aa3b, v116
	v_add_f32_e32 v112, 1.0, v112
	v_rcp_f32_e32 v121, v112
	v_mul_f32_e32 v112, 0xbfb8aa3b, v114
	v_exp_f32_e32 v112, v112
	v_mul_f32_e32 v117, 0xbfb8aa3b, v117
	v_mul_f32_e32 v119, 0xbfb8aa3b, v119
	v_exp_f32_e32 v116, v116
	v_add_f32_e32 v112, 1.0, v112
	v_rcp_f32_e32 v122, v112
; __device__ __forceinline__ unsigned pk2(float lo, float hi) { const f32x2 v = {lo, hi}; return __builtin_bit_cast(unsigned, __builtin_convertvector(v, bf16x2_t)); }
; __device__ __forceinline__ float sigmoidf_(float x) { return __builtin_amdgcn_rcpf(1.f + __builtin_amdgcn_exp2f(-x * LOG2E)); }
; #define EPI_LOOP _Pragma("unroll") for (int ai = 0; ai < 2; ++ai) _Pragma("unroll") for (int m = 0; m < 4; ++m) _Pragma("unroll") for (int bj = 0; bj < 2; ++bj)
;     __device__ __forceinline__ void operator()(const f32x4 (&acc)[2][2][4][2], const Unit& un, int wr, int wc, int fr, int fq) const {
;     ...
;         EPI_LOOP { const int row = rbase + ai * 128 + m * 16, col = cw + bj * 128; const float r = rr[ai][m];
;             f32x4 v0 = acc[ai][bj][m][0] * r + s0[bj], v1 = acc[ai][bj][m][1] * r + s1[bj];
;             v0 = (f32x4){sigmoidf_(v0.x), sigmoidf_(v0.y), sigmoidf_(v0.z), sigmoidf_(v0.w)}; v1 = (f32x4){sigmoidf_(v1.x), sigmoidf_(v1.y), sigmoidf_(v1.z), sigmoidf_(v1.w)};
;             u32x4 w; w.x = pk2(v0.x, v0.y); w.y = pk2(v0.z, v0.w); w.z = pk2(v1.x, v1.y); w.w = pk2(v1.z, v1.w);
;             *(u32x4*)(o + (size_t)row * DFF + col) = w; }
	v_mul_f32_e32 v112, 0xbfb8aa3b, v115
	v_exp_f32_e32 v117, v117
	v_exp_f32_e32 v118, v118
	v_exp_f32_e32 v119, v119
	v_exp_f32_e32 v112, v112
	v_pk_fma_f32 v[104:105], v[104:105], v[166:167], v[64:65] op_sel_hi:[1,0,1]
	v_add_f32_e32 v116, 1.0, v116
	v_add_f32_e32 v117, 1.0, v117
	v_add_f32_e32 v118, 1.0, v118
	v_add_f32_e32 v119, 1.0, v119
	v_add_f32_e32 v112, 1.0, v112
	v_mul_f32_e32 v104, 0xbfb8aa3b, v104
	v_rcp_f32_e32 v116, v116
	v_rcp_f32_e32 v117, v117
	v_rcp_f32_e32 v118, v118
	v_rcp_f32_e32 v119, v119
	v_rcp_f32_e32 v115, v112
	v_exp_f32_e32 v104, v104
	v_cvt_pk_bf16_f32 v112, v116, v117
	v_cvt_pk_bf16_f32 v113, v118, v119
	v_cvt_pk_bf16_f32 v114, v120, v121
	v_cvt_pk_bf16_f32 v115, v122, v115
	v_add_f32_e32 v104, 1.0, v104
	global_store_dwordx4 v[124:125], v[112:115], off offset:256
	v_pk_fma_f32 v[106:107], v[106:107], v[166:167], v[66:67] op_sel_hi:[1,0,1]
	v_pk_fma_f32 v[108:109], v[108:109], v[166:167], v[68:69] op_sel_hi:[1,0,1]
	v_rcp_f32_e32 v114, v104
	v_mul_f32_e32 v104, 0xbfb8aa3b, v105
	v_exp_f32_e32 v104, v104
	v_pk_fma_f32 v[110:111], v[110:111], v[166:167], v[70:71] op_sel_hi:[1,0,1]
	v_mul_f32_e32 v108, 0xbfb8aa3b, v108
	v_mul_f32_e32 v109, 0xbfb8aa3b, v109
	v_add_f32_e32 v104, 1.0, v104
	v_rcp_f32_e32 v115, v104
	v_mul_f32_e32 v104, 0xbfb8aa3b, v106
	v_exp_f32_e32 v104, v104
	v_exp_f32_e32 v108, v108
	v_exp_f32_e32 v109, v109
	v_mul_f32_e32 v110, 0xbfb8aa3b, v110
	v_add_f32_e32 v104, 1.0, v104
	v_mul_f32_e32 v111, 0xbfb8aa3b, v111
	v_rcp_f32_e32 v116, v104
	v_mul_f32_e32 v104, 0xbfb8aa3b, v107
	v_exp_f32_e32 v110, v110
	v_exp_f32_e32 v111, v111
	v_exp_f32_e32 v104, v104
	v_add_f32_e32 v108, 1.0, v108
	v_add_f32_e32 v109, 1.0, v109
	v_pk_fma_f32 v[96:97], v[96:97], v[166:167], v[48:49] op_sel_hi:[1,0,1]
	v_rcp_f32_e32 v108, v108
	v_rcp_f32_e32 v109, v109
	v_add_f32_e32 v110, 1.0, v110
	v_add_f32_e32 v111, 1.0, v111
	v_add_f32_e32 v104, 1.0, v104
	v_mul_f32_e32 v96, 0xbfb8aa3b, v96
	v_rcp_f32_e32 v110, v110
	v_rcp_f32_e32 v111, v111
	v_rcp_f32_e32 v107, v104
	v_exp_f32_e32 v96, v96
	v_lshlrev_b64 v[112:113], 14, v[168:169]
	v_cvt_pk_bf16_f32 v104, v108, v109
	v_lshl_add_u64 v[108:109], s[4:5], 0, v[112:113]
	v_cvt_pk_bf16_f32 v105, v110, v111
	v_cvt_pk_bf16_f32 v106, v114, v115
	v_cvt_pk_bf16_f32 v107, v116, v107
	v_lshl_add_u64 v[108:109], v[108:109], 0, v[138:139]
	v_add_f32_e32 v96, 1.0, v96
	global_store_dwordx4 v[108:109], v[104:107], off
	v_pk_fma_f32 v[98:99], v[98:99], v[166:167], v[50:51] op_sel_hi:[1,0,1]
	v_pk_fma_f32 v[102:103], v[102:103], v[166:167], v[54:55] op_sel_hi:[1,0,1]
	v_rcp_f32_e32 v104, v96
	v_mul_f32_e32 v96, 0xbfb8aa3b, v97
	v_exp_f32_e32 v96, v96
	v_pk_fma_f32 v[100:101], v[100:101], v[166:167], v[52:53] op_sel_hi:[1,0,1]
	v_mul_f32_e32 v102, 0xbfb8aa3b, v102
	v_mul_f32_e32 v100, 0xbfb8aa3b, v100
	v_add_f32_e32 v96, 1.0, v96
	v_rcp_f32_e32 v105, v96
	v_mul_f32_e32 v96, 0xbfb8aa3b, v98
	v_exp_f32_e32 v96, v96
	v_mul_f32_e32 v101, 0xbfb8aa3b, v101
	v_mul_f32_e32 v103, 0xbfb8aa3b, v103
	v_exp_f32_e32 v100, v100
	v_add_f32_e32 v96, 1.0, v96
	v_rcp_f32_e32 v106, v96
	v_mul_f32_e32 v96, 0xbfb8aa3b, v99
	v_exp_f32_e32 v101, v101
	v_exp_f32_e32 v102, v102
	v_exp_f32_e32 v103, v103
	v_exp_f32_e32 v96, v96
	v_pk_fma_f32 v[88:89], v[88:89], v[162:163], v[64:65] op_sel_hi:[1,0,1]
	v_add_f32_e32 v100, 1.0, v100
	v_add_f32_e32 v101, 1.0, v101
	v_add_f32_e32 v102, 1.0, v102
	v_add_f32_e32 v103, 1.0, v103
	v_add_f32_e32 v96, 1.0, v96
	v_mul_f32_e32 v88, 0xbfb8aa3b, v88
	v_rcp_f32_e32 v100, v100
	v_rcp_f32_e32 v101, v101
	v_rcp_f32_e32 v102, v102
	v_rcp_f32_e32 v103, v103
	v_rcp_f32_e32 v99, v96
	v_exp_f32_e32 v88, v88
	v_cvt_pk_bf16_f32 v96, v100, v101
	v_cvt_pk_bf16_f32 v97, v102, v103
	v_cvt_pk_bf16_f32 v98, v104, v105
	v_cvt_pk_bf16_f32 v99, v106, v99
	v_add_f32_e32 v88, 1.0, v88
	global_store_dwordx4 v[108:109], v[96:99], off offset:256
	v_pk_fma_f32 v[90:91], v[90:91], v[162:163], v[66:67] op_sel_hi:[1,0,1]
	v_pk_fma_f32 v[92:93], v[92:93], v[162:163], v[68:69] op_sel_hi:[1,0,1]
	v_rcp_f32_e32 v98, v88
	v_mul_f32_e32 v88, 0xbfb8aa3b, v89
	v_exp_f32_e32 v88, v88
	v_pk_fma_f32 v[94:95], v[94:95], v[162:163], v[70:71] op_sel_hi:[1,0,1]
	v_mul_f32_e32 v92, 0xbfb8aa3b, v92
	v_mul_f32_e32 v93, 0xbfb8aa3b, v93
	v_add_f32_e32 v88, 1.0, v88
	v_rcp_f32_e32 v99, v88
	v_mul_f32_e32 v88, 0xbfb8aa3b, v90
	v_exp_f32_e32 v88, v88
	v_exp_f32_e32 v92, v92
	v_exp_f32_e32 v93, v93
	v_mul_f32_e32 v94, 0xbfb8aa3b, v94
	v_add_f32_e32 v88, 1.0, v88
	v_mul_f32_e32 v95, 0xbfb8aa3b, v95
	v_rcp_f32_e32 v100, v88
	v_mul_f32_e32 v88, 0xbfb8aa3b, v91
	v_exp_f32_e32 v94, v94
	v_exp_f32_e32 v95, v95
	v_exp_f32_e32 v88, v88
	v_add_f32_e32 v92, 1.0, v92
	v_add_f32_e32 v93, 1.0, v93
	v_pk_fma_f32 v[80:81], v[80:81], v[162:163], v[48:49] op_sel_hi:[1,0,1]
	v_rcp_f32_e32 v92, v92
	v_rcp_f32_e32 v93, v93
	v_add_f32_e32 v94, 1.0, v94
	v_add_f32_e32 v95, 1.0, v95
	v_add_f32_e32 v88, 1.0, v88
	v_mul_f32_e32 v80, 0xbfb8aa3b, v80
	v_rcp_f32_e32 v94, v94
	v_rcp_f32_e32 v95, v95
	v_rcp_f32_e32 v91, v88
	v_exp_f32_e32 v80, v80
	v_lshlrev_b64 v[96:97], 14, v[164:165]
	v_cvt_pk_bf16_f32 v88, v92, v93
	v_lshl_add_u64 v[92:93], s[4:5], 0, v[96:97]
	v_cvt_pk_bf16_f32 v89, v94, v95
	v_cvt_pk_bf16_f32 v90, v98, v99
	v_cvt_pk_bf16_f32 v91, v100, v91
	v_lshl_add_u64 v[92:93], v[92:93], 0, v[138:139]
	v_add_f32_e32 v80, 1.0, v80
	global_store_dwordx4 v[92:93], v[88:91], off
	v_pk_fma_f32 v[82:83], v[82:83], v[162:163], v[50:51] op_sel_hi:[1,0,1]
	v_pk_fma_f32 v[86:87], v[86:87], v[162:163], v[54:55] op_sel_hi:[1,0,1]
	v_rcp_f32_e32 v88, v80
	v_mul_f32_e32 v80, 0xbfb8aa3b, v81
	v_exp_f32_e32 v80, v80
	v_pk_fma_f32 v[84:85], v[84:85], v[162:163], v[52:53] op_sel_hi:[1,0,1]
; __device__ __forceinline__ unsigned pk2(float lo, float hi) { const f32x2 v = {lo, hi}; return __builtin_bit_cast(unsigned, __builtin_convertvector(v, bf16x2_t)); }
; __device__ __forceinline__ float sigmoidf_(float x) { return __builtin_amdgcn_rcpf(1.f + __builtin_amdgcn_exp2f(-x * LOG2E)); }
; #define EPI_LOOP _Pragma("unroll") for (int ai = 0; ai < 2; ++ai) _Pragma("unroll") for (int m = 0; m < 4; ++m) _Pragma("unroll") for (int bj = 0; bj < 2; ++bj)
;     __device__ __forceinline__ void operator()(const f32x4 (&acc)[2][2][4][2], const Unit& un, int wr, int wc, int fr, int fq) const {
;     ...
;         EPI_LOOP { const int row = rbase + ai * 128 + m * 16, col = cw + bj * 128; const float r = rr[ai][m];
;             f32x4 v0 = acc[ai][bj][m][0] * r + s0[bj], v1 = acc[ai][bj][m][1] * r + s1[bj];
;             v0 = (f32x4){sigmoidf_(v0.x), sigmoidf_(v0.y), sigmoidf_(v0.z), sigmoidf_(v0.w)}; v1 = (f32x4){sigmoidf_(v1.x), sigmoidf_(v1.y), sigmoidf_(v1.z), sigmoidf_(v1.w)};
;             u32x4 w; w.x = pk2(v0.x, v0.y); w.y = pk2(v0.z, v0.w); w.z = pk2(v1.x, v1.y); w.w = pk2(v1.z, v1.w);
;             *(u32x4*)(o + (size_t)row * DFF + col) = w; }
	v_mul_f32_e32 v86, 0xbfb8aa3b, v86
	v_mul_f32_e32 v84, 0xbfb8aa3b, v84
	v_add_f32_e32 v80, 1.0, v80
	v_rcp_f32_e32 v89, v80
	v_mul_f32_e32 v80, 0xbfb8aa3b, v82
	v_exp_f32_e32 v80, v80
	v_mul_f32_e32 v85, 0xbfb8aa3b, v85
	v_mul_f32_e32 v87, 0xbfb8aa3b, v87
	v_exp_f32_e32 v84, v84
	v_add_f32_e32 v80, 1.0, v80
	v_rcp_f32_e32 v90, v80
	v_mul_f32_e32 v80, 0xbfb8aa3b, v83
	v_exp_f32_e32 v85, v85
	v_exp_f32_e32 v86, v86
	v_exp_f32_e32 v87, v87
	v_exp_f32_e32 v80, v80
	v_pk_fma_f32 v[72:73], v[72:73], v[160:161], v[64:65] op_sel_hi:[1,0,1]
	v_add_f32_e32 v84, 1.0, v84
	v_add_f32_e32 v85, 1.0, v85
	v_add_f32_e32 v86, 1.0, v86
	v_add_f32_e32 v87, 1.0, v87
	v_add_f32_e32 v80, 1.0, v80
	v_mul_f32_e32 v72, 0xbfb8aa3b, v72
	v_rcp_f32_e32 v84, v84
	v_rcp_f32_e32 v85, v85
	v_rcp_f32_e32 v86, v86
	v_rcp_f32_e32 v87, v87
	v_rcp_f32_e32 v83, v80
	v_exp_f32_e32 v72, v72
	v_cvt_pk_bf16_f32 v80, v84, v85
	v_cvt_pk_bf16_f32 v81, v86, v87
	v_cvt_pk_bf16_f32 v82, v88, v89
	v_cvt_pk_bf16_f32 v83, v90, v83
	v_add_f32_e32 v72, 1.0, v72
	global_store_dwordx4 v[92:93], v[80:83], off offset:256
	v_pk_fma_f32 v[74:75], v[74:75], v[160:161], v[66:67] op_sel_hi:[1,0,1]
	v_pk_fma_f32 v[78:79], v[78:79], v[160:161], v[70:71] op_sel_hi:[1,0,1]
	v_rcp_f32_e32 v80, v72
	v_mul_f32_e32 v72, 0xbfb8aa3b, v73
	v_exp_f32_e32 v72, v72
	v_pk_fma_f32 v[76:77], v[76:77], v[160:161], v[68:69] op_sel_hi:[1,0,1]
	v_mul_f32_e32 v78, 0xbfb8aa3b, v78
	v_mul_f32_e32 v79, 0xbfb8aa3b, v79
	v_add_f32_e32 v72, 1.0, v72
	v_rcp_f32_e32 v81, v72
	v_mul_f32_e32 v72, 0xbfb8aa3b, v74
	v_exp_f32_e32 v72, v72
	v_mul_f32_e32 v76, 0xbfb8aa3b, v76
	v_mul_f32_e32 v77, 0xbfb8aa3b, v77
	v_exp_f32_e32 v78, v78
	v_add_f32_e32 v72, 1.0, v72
	v_exp_f32_e32 v79, v79
	v_rcp_f32_e32 v82, v72
	v_mul_f32_e32 v72, 0xbfb8aa3b, v75
	v_exp_f32_e32 v76, v76
	v_exp_f32_e32 v77, v77
	v_exp_f32_e32 v72, v72
	v_add_f32_e32 v78, 1.0, v78
	v_add_f32_e32 v79, 1.0, v79
	v_pk_fma_f32 v[56:57], v[56:57], v[160:161], v[48:49] op_sel_hi:[1,0,1]
	v_add_f32_e32 v76, 1.0, v76
	v_add_f32_e32 v77, 1.0, v77
	v_rcp_f32_e32 v78, v78
	v_rcp_f32_e32 v79, v79
	v_add_f32_e32 v72, 1.0, v72
	v_mul_f32_e32 v56, 0xbfb8aa3b, v56
	v_rcp_f32_e32 v76, v76
	v_rcp_f32_e32 v77, v77
	v_rcp_f32_e32 v75, v72
	v_exp_f32_e32 v56, v56
	v_cvt_pk_bf16_f32 v73, v78, v79
	v_add_co_u32_e32 v78, vcc, s78, v136
	v_cvt_pk_bf16_f32 v72, v76, v77
	v_cvt_pk_bf16_f32 v74, v80, v81
	v_cvt_pk_bf16_f32 v75, v82, v75
	v_addc_co_u32_e32 v79, vcc, 0, v137, vcc
	v_add_f32_e32 v56, 1.0, v56
	global_store_dwordx4 v[78:79], v[72:75], off
	v_pk_fma_f32 v[58:59], v[58:59], v[160:161], v[50:51] op_sel_hi:[1,0,1]
	v_pk_fma_f32 v[62:63], v[62:63], v[160:161], v[54:55] op_sel_hi:[1,0,1]
	v_rcp_f32_e32 v72, v56
	v_mul_f32_e32 v56, 0xbfb8aa3b, v57
	v_exp_f32_e32 v56, v56
	v_pk_fma_f32 v[60:61], v[60:61], v[160:161], v[52:53] op_sel_hi:[1,0,1]
	v_mul_f32_e32 v62, 0xbfb8aa3b, v62
	v_mul_f32_e32 v60, 0xbfb8aa3b, v60
	v_add_f32_e32 v56, 1.0, v56
	v_rcp_f32_e32 v73, v56
	v_mul_f32_e32 v56, 0xbfb8aa3b, v58
	v_exp_f32_e32 v56, v56
	v_mul_f32_e32 v61, 0xbfb8aa3b, v61
	v_mul_f32_e32 v63, 0xbfb8aa3b, v63
	v_exp_f32_e32 v60, v60
	v_add_f32_e32 v56, 1.0, v56
	v_rcp_f32_e32 v74, v56
	v_mul_f32_e32 v56, 0xbfb8aa3b, v59
	v_exp_f32_e32 v61, v61
	v_exp_f32_e32 v62, v62
	v_exp_f32_e32 v63, v63
	v_exp_f32_e32 v56, v56
	v_pk_fma_f32 v[40:41], v[40:41], v[158:159], v[64:65] op_sel_hi:[1,0,1]
	v_add_f32_e32 v60, 1.0, v60
	v_add_f32_e32 v61, 1.0, v61
	v_add_f32_e32 v62, 1.0, v62
	v_add_f32_e32 v63, 1.0, v63
	v_add_f32_e32 v56, 1.0, v56
	v_mul_f32_e32 v40, 0xbfb8aa3b, v40
	v_rcp_f32_e32 v60, v60
	v_rcp_f32_e32 v61, v61
	v_rcp_f32_e32 v62, v62
	v_rcp_f32_e32 v63, v63
	v_rcp_f32_e32 v59, v56
	v_exp_f32_e32 v40, v40
	v_lshl_add_u64 v[76:77], v[136:137], 0, s[56:57]
	v_cvt_pk_bf16_f32 v56, v60, v61
	v_cvt_pk_bf16_f32 v57, v62, v63
	v_cvt_pk_bf16_f32 v58, v72, v73
	v_cvt_pk_bf16_f32 v59, v74, v59
	v_add_f32_e32 v40, 1.0, v40
	global_store_dwordx4 v[76:77], v[56:59], off offset:256
	v_pk_fma_f32 v[42:43], v[42:43], v[158:159], v[66:67] op_sel_hi:[1,0,1]
	v_pk_fma_f32 v[46:47], v[46:47], v[158:159], v[70:71] op_sel_hi:[1,0,1]
	v_rcp_f32_e32 v56, v40
	v_mul_f32_e32 v40, 0xbfb8aa3b, v41
	v_exp_f32_e32 v40, v40
	v_pk_fma_f32 v[44:45], v[44:45], v[158:159], v[68:69] op_sel_hi:[1,0,1]
	v_mul_f32_e32 v46, 0xbfb8aa3b, v46
	v_mul_f32_e32 v47, 0xbfb8aa3b, v47
	v_add_f32_e32 v40, 1.0, v40
	v_rcp_f32_e32 v57, v40
	v_mul_f32_e32 v40, 0xbfb8aa3b, v42
	v_exp_f32_e32 v40, v40
	v_mul_f32_e32 v44, 0xbfb8aa3b, v44
	v_mul_f32_e32 v45, 0xbfb8aa3b, v45
	v_exp_f32_e32 v46, v46
	v_add_f32_e32 v40, 1.0, v40
	v_exp_f32_e32 v47, v47
	v_rcp_f32_e32 v58, v40
	v_mul_f32_e32 v40, 0xbfb8aa3b, v43
	v_exp_f32_e32 v44, v44
	v_exp_f32_e32 v45, v45
	v_exp_f32_e32 v40, v40
	v_add_f32_e32 v46, 1.0, v46
	v_add_f32_e32 v47, 1.0, v47
	v_pk_fma_f32 v[32:33], v[32:33], v[158:159], v[48:49] op_sel_hi:[1,0,1]
	v_add_f32_e32 v44, 1.0, v44
	v_add_f32_e32 v45, 1.0, v45
	v_rcp_f32_e32 v46, v46
	v_rcp_f32_e32 v47, v47
	v_add_f32_e32 v40, 1.0, v40
	v_mul_f32_e32 v32, 0xbfb8aa3b, v32
	v_rcp_f32_e32 v44, v44
	v_rcp_f32_e32 v45, v45
	v_rcp_f32_e32 v43, v40
	v_exp_f32_e32 v32, v32
	v_cvt_pk_bf16_f32 v41, v46, v47
	v_add_co_u32_e32 v46, vcc, s74, v136
	v_cvt_pk_bf16_f32 v40, v44, v45
	v_cvt_pk_bf16_f32 v42, v56, v57
	v_cvt_pk_bf16_f32 v43, v58, v43
	v_addc_co_u32_e32 v47, vcc, 0, v137, vcc
	v_add_f32_e32 v32, 1.0, v32
	global_store_dwordx4 v[46:47], v[40:43], off
	v_pk_fma_f32 v[34:35], v[34:35], v[158:159], v[50:51] op_sel_hi:[1,0,1]
	v_pk_fma_f32 v[38:39], v[38:39], v[158:159], v[54:55] op_sel_hi:[1,0,1]
	v_rcp_f32_e32 v40, v32
	v_mul_f32_e32 v32, 0xbfb8aa3b, v33
; #define PG8_BAR __builtin_amdgcn_s_barrier()
; __device__ __forceinline__ unsigned pk2(float lo, float hi) { const f32x2 v = {lo, hi}; return __builtin_bit_cast(unsigned, __builtin_convertvector(v, bf16x2_t)); }
; __device__ __forceinline__ float sigmoidf_(float x) { return __builtin_amdgcn_rcpf(1.f + __builtin_amdgcn_exp2f(-x * LOG2E)); }
; #define EPI_LOOP _Pragma("unroll") for (int ai = 0; ai < 2; ++ai) _Pragma("unroll") for (int m = 0; m < 4; ++m) _Pragma("unroll") for (int bj = 0; bj < 2; ++bj)
; template <class Epi, class Sched, bool ALIGN_EPI = false, bool SP2 = false>
; __device__ __forceinline__ void gemm_phase(PG8_LAS unsigned char* lds, const Gemm g, const Sched& S, const Epi& E, const int tid) {
;     ...
;         if constexpr (!Epi::AFTER_DRAIN) { E(acc, cur, wr, wc, fr, fq); S.done(cur); }
;         if (!has_next) break;
; #pragma unroll
;         for (int a = 0; a < 2; ++a)
; #pragma unroll
;             for (int b = 0; b < 2; ++b)
; #pragma unroll
;                 for (int m = 0; m < 4; ++m)
; #pragma unroll
;                     for (int n = 0; n < 2; ++n) acc[a][b][m][n] = (f32x4){0.f, 0.f, 0.f, 0.f};
;         cur = nxt; cA = nA; cB = nB; ++ui;
;         if constexpr (ALIGN_EPI) { if (wr == 1) PG8_BAR; }
;     }
;     __device__ __forceinline__ void operator()(const f32x4 (&acc)[2][2][4][2], const Unit& un, int wr, int wc, int fr, int fq) const {
;     ...
;         EPI_LOOP { const int row = rbase + ai * 128 + m * 16, col = cw + bj * 128; const float r = rr[ai][m];
;             f32x4 v0 = acc[ai][bj][m][0] * r + s0[bj], v1 = acc[ai][bj][m][1] * r + s1[bj];
;             v0 = (f32x4){sigmoidf_(v0.x), sigmoidf_(v0.y), sigmoidf_(v0.z), sigmoidf_(v0.w)}; v1 = (f32x4){sigmoidf_(v1.x), sigmoidf_(v1.y), sigmoidf_(v1.z), sigmoidf_(v1.w)};
;             u32x4 w; w.x = pk2(v0.x, v0.y); w.y = pk2(v0.z, v0.w); w.z = pk2(v1.x, v1.y); w.w = pk2(v1.z, v1.w);
;             *(u32x4*)(o + (size_t)row * DFF + col) = w; }
	v_exp_f32_e32 v32, v32
	v_pk_fma_f32 v[36:37], v[36:37], v[158:159], v[52:53] op_sel_hi:[1,0,1]
	v_mul_f32_e32 v38, 0xbfb8aa3b, v38
	v_mul_f32_e32 v36, 0xbfb8aa3b, v36
	v_add_f32_e32 v32, 1.0, v32
	v_rcp_f32_e32 v41, v32
	v_mul_f32_e32 v32, 0xbfb8aa3b, v34
	v_exp_f32_e32 v32, v32
	v_mul_f32_e32 v37, 0xbfb8aa3b, v37
	v_mul_f32_e32 v39, 0xbfb8aa3b, v39
	v_exp_f32_e32 v36, v36
	v_add_f32_e32 v32, 1.0, v32
	v_rcp_f32_e32 v42, v32
	v_mul_f32_e32 v32, 0xbfb8aa3b, v35
	v_exp_f32_e32 v37, v37
	v_exp_f32_e32 v38, v38
	v_exp_f32_e32 v39, v39
	v_exp_f32_e32 v32, v32
	v_pk_fma_f32 v[24:25], v[24:25], v[156:157], v[64:65] op_sel_hi:[1,0,1]
	v_add_f32_e32 v36, 1.0, v36
	v_add_f32_e32 v37, 1.0, v37
	v_add_f32_e32 v38, 1.0, v38
	v_add_f32_e32 v39, 1.0, v39
	v_add_f32_e32 v32, 1.0, v32
	v_mul_f32_e32 v24, 0xbfb8aa3b, v24
	v_rcp_f32_e32 v36, v36
	v_rcp_f32_e32 v37, v37
	v_rcp_f32_e32 v38, v38
	v_rcp_f32_e32 v39, v39
	v_rcp_f32_e32 v35, v32
	v_exp_f32_e32 v24, v24
	v_lshl_add_u64 v[44:45], v[136:137], 0, s[20:21]
	v_cvt_pk_bf16_f32 v32, v36, v37
	v_cvt_pk_bf16_f32 v33, v38, v39
	v_cvt_pk_bf16_f32 v34, v40, v41
	v_cvt_pk_bf16_f32 v35, v42, v35
	v_add_f32_e32 v24, 1.0, v24
	global_store_dwordx4 v[44:45], v[32:35], off offset:256
	v_pk_fma_f32 v[26:27], v[26:27], v[156:157], v[66:67] op_sel_hi:[1,0,1]
	v_pk_fma_f32 v[30:31], v[30:31], v[156:157], v[70:71] op_sel_hi:[1,0,1]
	v_rcp_f32_e32 v32, v24
	v_mul_f32_e32 v24, 0xbfb8aa3b, v25
	v_exp_f32_e32 v24, v24
	v_pk_fma_f32 v[28:29], v[28:29], v[156:157], v[68:69] op_sel_hi:[1,0,1]
	v_mul_f32_e32 v30, 0xbfb8aa3b, v30
	v_mul_f32_e32 v31, 0xbfb8aa3b, v31
	v_add_f32_e32 v24, 1.0, v24
	v_rcp_f32_e32 v33, v24
	v_mul_f32_e32 v24, 0xbfb8aa3b, v26
	v_exp_f32_e32 v24, v24
	v_mul_f32_e32 v28, 0xbfb8aa3b, v28
	v_mul_f32_e32 v29, 0xbfb8aa3b, v29
	v_exp_f32_e32 v30, v30
	v_add_f32_e32 v24, 1.0, v24
	v_exp_f32_e32 v31, v31
	v_rcp_f32_e32 v34, v24
	v_mul_f32_e32 v24, 0xbfb8aa3b, v27
	v_exp_f32_e32 v28, v28
	v_exp_f32_e32 v29, v29
	v_exp_f32_e32 v24, v24
	v_add_f32_e32 v30, 1.0, v30
	v_add_f32_e32 v31, 1.0, v31
	v_pk_fma_f32 v[16:17], v[16:17], v[156:157], v[48:49] op_sel_hi:[1,0,1]
	v_add_f32_e32 v28, 1.0, v28
	v_add_f32_e32 v29, 1.0, v29
	v_rcp_f32_e32 v30, v30
	v_rcp_f32_e32 v31, v31
	v_add_f32_e32 v24, 1.0, v24
	v_mul_f32_e32 v16, 0xbfb8aa3b, v16
	v_rcp_f32_e32 v28, v28
	v_rcp_f32_e32 v29, v29
	v_rcp_f32_e32 v27, v24
	v_exp_f32_e32 v16, v16
	v_cvt_pk_bf16_f32 v25, v30, v31
	v_add_co_u32_e32 v30, vcc, s71, v136
	v_cvt_pk_bf16_f32 v24, v28, v29
	v_cvt_pk_bf16_f32 v26, v32, v33
	v_cvt_pk_bf16_f32 v27, v34, v27
	v_addc_co_u32_e32 v31, vcc, 0, v137, vcc
	v_add_f32_e32 v16, 1.0, v16
	global_store_dwordx4 v[30:31], v[24:27], off
	v_pk_fma_f32 v[18:19], v[18:19], v[156:157], v[50:51] op_sel_hi:[1,0,1]
	v_pk_fma_f32 v[22:23], v[22:23], v[156:157], v[54:55] op_sel_hi:[1,0,1]
	v_rcp_f32_e32 v24, v16
	v_mul_f32_e32 v16, 0xbfb8aa3b, v17
	v_exp_f32_e32 v16, v16
	v_pk_fma_f32 v[20:21], v[20:21], v[156:157], v[52:53] op_sel_hi:[1,0,1]
	v_mul_f32_e32 v22, 0xbfb8aa3b, v22
	v_mul_f32_e32 v20, 0xbfb8aa3b, v20
	v_add_f32_e32 v16, 1.0, v16
	v_rcp_f32_e32 v25, v16
	v_mul_f32_e32 v16, 0xbfb8aa3b, v18
	v_exp_f32_e32 v16, v16
	v_mul_f32_e32 v21, 0xbfb8aa3b, v21
	v_mul_f32_e32 v23, 0xbfb8aa3b, v23
	v_exp_f32_e32 v20, v20
	v_add_f32_e32 v16, 1.0, v16
	v_rcp_f32_e32 v26, v16
	v_mul_f32_e32 v16, 0xbfb8aa3b, v19
	v_exp_f32_e32 v21, v21
	v_exp_f32_e32 v22, v22
	v_exp_f32_e32 v23, v23
	v_exp_f32_e32 v16, v16
	v_pk_fma_f32 v[8:9], v[8:9], v[154:155], v[64:65] op_sel_hi:[1,0,1]
	v_add_f32_e32 v20, 1.0, v20
	v_add_f32_e32 v21, 1.0, v21
	v_add_f32_e32 v22, 1.0, v22
	v_add_f32_e32 v23, 1.0, v23
	v_add_f32_e32 v16, 1.0, v16
	v_mul_f32_e32 v8, 0xbfb8aa3b, v8
	v_rcp_f32_e32 v20, v20
	v_rcp_f32_e32 v21, v21
	v_rcp_f32_e32 v22, v22
	v_rcp_f32_e32 v23, v23
	v_rcp_f32_e32 v19, v16
	v_exp_f32_e32 v8, v8
	s_mov_b64 s[20:21], 0x280000
	v_lshl_add_u64 v[28:29], v[136:137], 0, s[20:21]
	v_cvt_pk_bf16_f32 v16, v20, v21
	v_cvt_pk_bf16_f32 v17, v22, v23
	v_cvt_pk_bf16_f32 v18, v24, v25
	v_cvt_pk_bf16_f32 v19, v26, v19
	v_add_f32_e32 v8, 1.0, v8
	global_store_dwordx4 v[28:29], v[16:19], off offset:256
	v_pk_fma_f32 v[10:11], v[10:11], v[154:155], v[66:67] op_sel_hi:[1,0,1]
	v_pk_fma_f32 v[14:15], v[14:15], v[154:155], v[70:71] op_sel_hi:[1,0,1]
	v_rcp_f32_e32 v16, v8
	v_mul_f32_e32 v8, 0xbfb8aa3b, v9
	v_exp_f32_e32 v8, v8
	v_pk_fma_f32 v[12:13], v[12:13], v[154:155], v[68:69] op_sel_hi:[1,0,1]
	v_mul_f32_e32 v14, 0xbfb8aa3b, v14
	v_mul_f32_e32 v15, 0xbfb8aa3b, v15
	v_add_f32_e32 v8, 1.0, v8
	v_rcp_f32_e32 v17, v8
	v_mul_f32_e32 v8, 0xbfb8aa3b, v10
	v_exp_f32_e32 v8, v8
	v_mul_f32_e32 v12, 0xbfb8aa3b, v12
	v_mul_f32_e32 v13, 0xbfb8aa3b, v13
	v_exp_f32_e32 v14, v14
	v_add_f32_e32 v8, 1.0, v8
	v_exp_f32_e32 v15, v15
	v_rcp_f32_e32 v18, v8
	v_mul_f32_e32 v8, 0xbfb8aa3b, v11
	v_exp_f32_e32 v12, v12
	v_exp_f32_e32 v13, v13
	v_exp_f32_e32 v8, v8
	v_add_f32_e32 v14, 1.0, v14
	v_add_f32_e32 v15, 1.0, v15
	v_pk_fma_f32 v[0:1], v[0:1], v[154:155], v[48:49] op_sel_hi:[1,0,1]
	v_add_f32_e32 v12, 1.0, v12
	v_add_f32_e32 v13, 1.0, v13
	v_rcp_f32_e32 v14, v14
	v_rcp_f32_e32 v15, v15
	v_add_f32_e32 v8, 1.0, v8
	v_mul_f32_e32 v0, 0xbfb8aa3b, v0
	v_rcp_f32_e32 v12, v12
	v_rcp_f32_e32 v13, v13
	v_rcp_f32_e32 v11, v8
	v_exp_f32_e32 v0, v0
	v_cvt_pk_bf16_f32 v9, v14, v15
	v_add_co_u32_e32 v14, vcc, s72, v136
	v_cvt_pk_bf16_f32 v8, v12, v13
	v_cvt_pk_bf16_f32 v10, v16, v17
	v_cvt_pk_bf16_f32 v11, v18, v11
	v_addc_co_u32_e32 v15, vcc, 0, v137, vcc
	v_add_f32_e32 v0, 1.0, v0
	global_store_dwordx4 v[14:15], v[8:11], off
	v_pk_fma_f32 v[2:3], v[2:3], v[154:155], v[50:51] op_sel_hi:[1,0,1]
	v_pk_fma_f32 v[6:7], v[6:7], v[154:155], v[54:55] op_sel_hi:[1,0,1]
	v_rcp_f32_e32 v8, v0
	v_mul_f32_e32 v0, 0xbfb8aa3b, v1
	v_exp_f32_e32 v0, v0
	v_pk_fma_f32 v[4:5], v[4:5], v[154:155], v[52:53] op_sel_hi:[1,0,1]
	v_mul_f32_e32 v6, 0xbfb8aa3b, v6
	v_mul_f32_e32 v4, 0xbfb8aa3b, v4
	v_add_f32_e32 v0, 1.0, v0
	v_rcp_f32_e32 v9, v0
	v_mul_f32_e32 v0, 0xbfb8aa3b, v2
	v_exp_f32_e32 v0, v0
	v_mul_f32_e32 v5, 0xbfb8aa3b, v5
	v_mul_f32_e32 v7, 0xbfb8aa3b, v7
	v_exp_f32_e32 v4, v4
	v_add_f32_e32 v0, 1.0, v0
	v_rcp_f32_e32 v10, v0
	v_mul_f32_e32 v0, 0xbfb8aa3b, v3
	v_exp_f32_e32 v5, v5
	v_exp_f32_e32 v6, v6
	v_exp_f32_e32 v7, v7
	v_exp_f32_e32 v0, v0
	v_add_f32_e32 v4, 1.0, v4
	v_add_f32_e32 v5, 1.0, v5
	v_add_f32_e32 v6, 1.0, v6
	v_add_f32_e32 v7, 1.0, v7
	v_add_f32_e32 v0, 1.0, v0
	v_rcp_f32_e32 v4, v4
	v_rcp_f32_e32 v5, v5
	v_rcp_f32_e32 v6, v6
	v_rcp_f32_e32 v7, v7
	v_rcp_f32_e32 v3, v0
	s_mov_b64 s[20:21], 0x2c0000
	v_lshl_add_u64 v[12:13], v[136:137], 0, s[20:21]
	v_cvt_pk_bf16_f32 v0, v4, v5
	v_cvt_pk_bf16_f32 v1, v6, v7
	v_cvt_pk_bf16_f32 v2, v8, v9
	v_cvt_pk_bf16_f32 v3, v10, v3
	s_mov_b64 s[20:21], -1
	s_andn2_b64 vcc, exec, s[12:13]
	global_store_dwordx4 v[12:13], v[0:3], off offset:256
	s_cbranch_vccnz .LBB0_764
	s_andn2_b64 vcc, exec, s[0:1]
	s_cbranch_vccnz .LBB0_763
	s_barrier
	s_branch .LBB0_763

; #define PG8_STAGE(bufoff, gbase, voff) do { _Pragma("unroll") for (int _i = 0; _i < 2; ++_i) \
;         __builtin_amdgcn_global_load_lds((const unsigned*)((const char*)(gbase) + (voff)[_i]), (PG8_LAS unsigned*)(lds + (bufoff) + ldsw + _i * 8192), 16, 0, 0); } while (0)
; #define PG8_LDA(dst, b, h) do { _Pragma("unroll") for (int m = 0; m < 4; ++m) _Pragma("unroll") for (int k = 0; k < 2; ++k) dst[m][k] = *(const PG8_LAS bf16x8*)(lds + PG8_SA(b, h) + aoff + m * 2048 + k * 1024); } while (0)
; #define PG8_LDB(dst, b, h) do { _Pragma("unroll") for (int n = 0; n < 2; ++n) _Pragma("unroll") for (int k = 0; k < 2; ++k) dst[n][k] = *(const PG8_LAS bf16x8*)(lds + PG8_SB(b, h) + boff + n * 2048 + k * 1024); } while (0)
; #define PG8_MMA(ai, bj, At, Bt) do { __builtin_amdgcn_s_setprio(1); _Pragma("unroll") for (int m = 0; m < 4; ++m) _Pragma("unroll") for (int n = 0; n < 2; ++n) _Pragma("unroll") for (int k = 0; k < 2; ++k) \
;         acc[ai][bj][m][n] = __builtin_amdgcn_mfma_f32_16x16x32_bf16(Bt[n][k], At[m][k], acc[ai][bj][m][n], 0, 0, 0); __builtin_amdgcn_s_setprio(0); } while (0)
; #define PG8_WAIT_V(n) asm volatile("s_waitcnt vmcnt(" #n ")" ::: "memory")
; #define PG8_WAIT_L(n) asm volatile("s_waitcnt lgkmcnt(" #n ")" ::: "memory")
; #define PG8_BAR __builtin_amdgcn_s_barrier()
; #define PG8_SCHED __builtin_amdgcn_sched_barrier(0)
; template <class Epi, class Sched, bool ALIGN_EPI = false, bool SP2 = false>
; __device__ __forceinline__ void gemm_phase(PG8_LAS unsigned char* lds, const Gemm g, const Sched& S, const Epi& E, const int tid) {
;     ...
;             PG8_LDB(B0, 0, 0); PG8_LDB(B1, 0, 1); PG8_SCHED; PG8_LDA(At, 0, 0); PG8_STAGE(PG8_SA(1, 1), a1 + hstep, voffA);
;             PG8_WAIT_V(8); PG8_WAIT_L(0); PG8_BAR; PG8_MMA(0, 0, At, B0); PG8_MMA(0, 1, At, B1); PG8_BAR; PG8_SCHED;
;             PG8_LDA(At, 0, 1); PG8_STAGE(PG8_SB(0, 0), b2, voffB); PG8_STAGE(PG8_SB(0, 1), b2 + hstep, voffB); PG8_STAGE(PG8_SA(0, 0), a2, voffA);
.LBB0_1047:
	s_add_u32 s26, s24, 0xfff80080
	s_addc_u32 s27, s25, -1
	s_add_i32 s51, 0, 0x10000
	v_add_u32_e32 v68, s51, v157
	v_add_u32_e32 v154, s33, v157
	ds_read_b128 v[48:51], v68
	ds_read_b128 v[52:55], v68 offset:1024
	ds_read_b128 v[64:67], v68 offset:2048
	ds_read_b128 v[68:71], v68 offset:3072
	ds_read_b128 v[162:165], v154
	ds_read_b128 v[166:169], v154 offset:1024
	ds_read_b128 v[170:173], v154 offset:2048
	ds_read_b128 v[174:177], v154 offset:3072
	s_cmp_eq_u32 s50, 28
	s_cselect_b32 s29, s15, s27
	s_cselect_b32 s28, s21, s26
	s_cselect_b32 s27, s11, s49
	s_cselect_b32 s26, s47, s48
	v_lshl_add_u64 v[206:207], s[24:25], 0, v[150:151]
	s_add_i32 m0, s23, 0xc000
	ds_read_b128 v[178:181], v161
	ds_read_b128 v[182:185], v161 offset:1024
	ds_read_b128 v[186:189], v161 offset:2048
	ds_read_b128 v[190:193], v161 offset:3072
	ds_read_b128 v[194:197], v161 offset:4096
	ds_read_b128 v[198:201], v161 offset:5120
	ds_read_b128 v[202:205], v161 offset:6144
	ds_read_b128 v[214:217], v161 offset:7168
	global_load_lds_dwordx4 v[206:207], off
	v_lshl_add_u64 v[206:207], s[24:25], 0, v[152:153]
	s_add_i32 m0, s23, 0xe000
	s_nop 0
	global_load_lds_dwordx4 v[206:207], off
	s_waitcnt vmcnt(8)
	s_waitcnt lgkmcnt(0)
	s_barrier
	s_setprio 1
	s_waitcnt lgkmcnt(0)
	v_mfma_f32_16x16x32_bf16 v[140:143], v[48:51], v[178:181], v[140:143]
	v_mfma_f32_16x16x32_bf16 v[136:139], v[64:67], v[178:181], v[136:139]
	v_mfma_f32_16x16x32_bf16 v[124:127], v[48:51], v[186:189], v[124:127]
	v_mfma_f32_16x16x32_bf16 v[120:123], v[64:67], v[186:189], v[120:123]
	v_mfma_f32_16x16x32_bf16 v[108:111], v[48:51], v[194:197], v[108:111]
	v_mfma_f32_16x16x32_bf16 v[104:107], v[64:67], v[194:197], v[104:107]
	v_mfma_f32_16x16x32_bf16 v[92:95], v[48:51], v[202:205], v[92:95]
	v_mfma_f32_16x16x32_bf16 v[88:91], v[64:67], v[202:205], v[88:91]
	v_mfma_f32_16x16x32_bf16 v[140:143], v[52:55], v[182:185], v[140:143]
	v_mfma_f32_16x16x32_bf16 v[136:139], v[68:71], v[182:185], v[136:139]
	v_mfma_f32_16x16x32_bf16 v[124:127], v[52:55], v[190:193], v[124:127]
	v_mfma_f32_16x16x32_bf16 v[120:123], v[68:71], v[190:193], v[120:123]
	v_mfma_f32_16x16x32_bf16 v[108:111], v[52:55], v[198:201], v[108:111]
	v_mfma_f32_16x16x32_bf16 v[104:107], v[68:71], v[198:201], v[104:107]
	v_mfma_f32_16x16x32_bf16 v[92:95], v[52:55], v[214:217], v[92:95]
	v_mfma_f32_16x16x32_bf16 v[88:91], v[68:71], v[214:217], v[88:91]
	s_setprio 0
	s_setprio 1
	v_mfma_f32_16x16x32_bf16 v[132:135], v[162:165], v[178:181], v[132:135]
	v_mfma_f32_16x16x32_bf16 v[128:131], v[170:173], v[178:181], v[128:131]
	v_mfma_f32_16x16x32_bf16 v[116:119], v[162:165], v[186:189], v[116:119]
	v_mfma_f32_16x16x32_bf16 v[112:115], v[170:173], v[186:189], v[112:115]
	v_mfma_f32_16x16x32_bf16 v[100:103], v[162:165], v[194:197], v[100:103]
	v_mfma_f32_16x16x32_bf16 v[96:99], v[170:173], v[194:197], v[96:99]
	v_mfma_f32_16x16x32_bf16 v[84:87], v[162:165], v[202:205], v[84:87]
	v_mfma_f32_16x16x32_bf16 v[80:83], v[170:173], v[202:205], v[80:83]
	v_mfma_f32_16x16x32_bf16 v[132:135], v[166:169], v[182:185], v[132:135]
	v_mfma_f32_16x16x32_bf16 v[128:131], v[174:177], v[182:185], v[128:131]
	v_mfma_f32_16x16x32_bf16 v[116:119], v[166:169], v[190:193], v[116:119]
	v_mfma_f32_16x16x32_bf16 v[112:115], v[174:177], v[190:193], v[112:115]
	v_mfma_f32_16x16x32_bf16 v[100:103], v[166:169], v[198:201], v[100:103]
	v_mfma_f32_16x16x32_bf16 v[96:99], v[174:177], v[198:201], v[96:99]
	v_mfma_f32_16x16x32_bf16 v[84:87], v[166:169], v[214:217], v[84:87]
	v_mfma_f32_16x16x32_bf16 v[80:83], v[174:177], v[214:217], v[80:83]
	s_setprio 0
	s_barrier
	s_add_i32 s51, s51, s38
	v_lshl_add_u64 v[206:207], s[26:27], 0, v[208:209]
	s_mov_b32 m0, s51
	ds_read_b128 v[178:181], v161 offset:16384
	ds_read_b128 v[182:185], v161 offset:17408
	ds_read_b128 v[186:189], v161 offset:18432
	ds_read_b128 v[190:193], v161 offset:19456
	ds_read_b128 v[194:197], v161 offset:20480
	ds_read_b128 v[198:201], v161 offset:21504
	ds_read_b128 v[202:205], v161 offset:22528
	ds_read_b128 v[214:217], v161 offset:23552
	global_load_lds_dwordx4 v[206:207], off
	s_add_i32 m0, s51, 0x2000
	s_add_u32 s52, s26, 0x80000
	v_lshl_add_u64 v[210:211], s[26:27], 0, v[144:145]
	s_addc_u32 s53, s27, 0
	s_add_i32 s51, s33, s38
	global_load_lds_dwordx4 v[210:211], off
	v_lshl_add_u64 v[218:219], s[52:53], 0, v[208:209]
	s_mov_b32 m0, s51
	v_lshl_add_u64 v[220:221], s[28:29], 0, v[146:147]
	global_load_lds_dwordx4 v[218:219], off
	v_lshl_add_u64 v[218:219], s[52:53], 0, v[144:145]
	s_add_i32 m0, s51, 0x2000
	s_nop 0
	global_load_lds_dwordx4 v[218:219], off
	v_lshl_add_u64 v[218:219], s[28:29], 0, v[148:149]
	s_mov_b32 m0, s23
	s_nop 0
	global_load_lds_dwordx4 v[218:219], off
	s_mov_b32 m0, s39
	s_nop 0
	global_load_lds_dwordx4 v[220:221], off
	s_waitcnt vmcnt(8)
	s_waitcnt lgkmcnt(0)
	s_barrier
; #define PG8_STAGE(bufoff, gbase, voff) do { _Pragma("unroll") for (int _i = 0; _i < 2; ++_i) \
;         __builtin_amdgcn_global_load_lds((const unsigned*)((const char*)(gbase) + (voff)[_i]), (PG8_LAS unsigned*)(lds + (bufoff) + ldsw + _i * 8192), 16, 0, 0); } while (0)
; #define PG8_LDA(dst, b, h) do { _Pragma("unroll") for (int m = 0; m < 4; ++m) _Pragma("unroll") for (int k = 0; k < 2; ++k) dst[m][k] = *(const PG8_LAS bf16x8*)(lds + PG8_SA(b, h) + aoff + m * 2048 + k * 1024); } while (0)
; #define PG8_LDB(dst, b, h) do { _Pragma("unroll") for (int n = 0; n < 2; ++n) _Pragma("unroll") for (int k = 0; k < 2; ++k) dst[n][k] = *(const PG8_LAS bf16x8*)(lds + PG8_SB(b, h) + boff + n * 2048 + k * 1024); } while (0)
; #define PG8_MMA(ai, bj, At, Bt) do { __builtin_amdgcn_s_setprio(1); _Pragma("unroll") for (int m = 0; m < 4; ++m) _Pragma("unroll") for (int n = 0; n < 2; ++n) _Pragma("unroll") for (int k = 0; k < 2; ++k) \
;         acc[ai][bj][m][n] = __builtin_amdgcn_mfma_f32_16x16x32_bf16(Bt[n][k], At[m][k], acc[ai][bj][m][n], 0, 0, 0); __builtin_amdgcn_s_setprio(0); } while (0)
; #define PG8_WAIT_V(n) asm volatile("s_waitcnt vmcnt(" #n ")" ::: "memory")
; #define PG8_WAIT_L(n) asm volatile("s_waitcnt lgkmcnt(" #n ")" ::: "memory")
; #define PG8_BAR __builtin_amdgcn_s_barrier()
; #define PG8_SCHED __builtin_amdgcn_sched_barrier(0)
; template <class Epi, class Sched, bool ALIGN_EPI = false, bool SP2 = false>
; __device__ __forceinline__ void gemm_phase(PG8_LAS unsigned char* lds, const Gemm g, const Sched& S, const Epi& E, const int tid) {
;     ...
;             PG8_WAIT_V(8); PG8_WAIT_L(0); PG8_BAR; PG8_MMA(1, 0, At, B0); PG8_MMA(1, 1, At, B1); PG8_BAR; PG8_SCHED;
;             PG8_LDB(B0, 1, 0); PG8_LDB(B1, 1, 1); PG8_SCHED; PG8_LDA(At, 1, 0); PG8_STAGE(PG8_SA(0, 1), a2 + hstep, voffA);
;             PG8_WAIT_V(8); PG8_WAIT_L(0); PG8_BAR; PG8_MMA(0, 0, At, B0); PG8_MMA(0, 1, At, B1); PG8_BAR; PG8_SCHED;
	s_setprio 1
	s_waitcnt lgkmcnt(0)
	v_mfma_f32_16x16x32_bf16 v[76:79], v[48:51], v[178:181], v[76:79]
	v_mfma_f32_16x16x32_bf16 v[72:75], v[64:67], v[178:181], v[72:75]
	v_mfma_f32_16x16x32_bf16 v[44:47], v[48:51], v[186:189], v[44:47]
	v_mfma_f32_16x16x32_bf16 v[40:43], v[64:67], v[186:189], v[40:43]
	v_mfma_f32_16x16x32_bf16 v[28:31], v[48:51], v[194:197], v[28:31]
	v_mfma_f32_16x16x32_bf16 v[24:27], v[64:67], v[194:197], v[24:27]
	v_mfma_f32_16x16x32_bf16 v[12:15], v[48:51], v[202:205], v[12:15]
	v_mfma_f32_16x16x32_bf16 v[8:11], v[64:67], v[202:205], v[8:11]
	v_mfma_f32_16x16x32_bf16 v[76:79], v[52:55], v[182:185], v[76:79]
	v_mfma_f32_16x16x32_bf16 v[72:75], v[68:71], v[182:185], v[72:75]
	v_mfma_f32_16x16x32_bf16 v[44:47], v[52:55], v[190:193], v[44:47]
	v_mfma_f32_16x16x32_bf16 v[40:43], v[68:71], v[190:193], v[40:43]
	v_mfma_f32_16x16x32_bf16 v[28:31], v[52:55], v[198:201], v[28:31]
	v_mfma_f32_16x16x32_bf16 v[24:27], v[68:71], v[198:201], v[24:27]
	v_mfma_f32_16x16x32_bf16 v[12:15], v[52:55], v[214:217], v[12:15]
	v_mfma_f32_16x16x32_bf16 v[8:11], v[68:71], v[214:217], v[8:11]
	s_setprio 0
	s_setprio 1
	v_mfma_f32_16x16x32_bf16 v[36:39], v[162:165], v[186:189], v[36:39]
	v_mfma_f32_16x16x32_bf16 v[32:35], v[170:173], v[186:189], v[32:35]
	v_mfma_f32_16x16x32_bf16 v[20:23], v[162:165], v[194:197], v[20:23]
	v_mfma_f32_16x16x32_bf16 v[16:19], v[170:173], v[194:197], v[16:19]
	v_mfma_f32_16x16x32_bf16 v[4:7], v[162:165], v[202:205], v[4:7]
	v_mfma_f32_16x16x32_bf16 v[0:3], v[170:173], v[202:205], v[0:3]
	v_mfma_f32_16x16x32_bf16 v[48:51], v[162:165], v[178:181], v[60:63]
	v_mfma_f32_16x16x32_bf16 v[52:55], v[170:173], v[178:181], v[56:59]
	v_mfma_f32_16x16x32_bf16 v[36:39], v[166:169], v[190:193], v[36:39]
	v_mfma_f32_16x16x32_bf16 v[32:35], v[174:177], v[190:193], v[32:35]
	v_mfma_f32_16x16x32_bf16 v[20:23], v[166:169], v[198:201], v[20:23]
	v_mfma_f32_16x16x32_bf16 v[16:19], v[174:177], v[198:201], v[16:19]
	v_mfma_f32_16x16x32_bf16 v[4:7], v[166:169], v[214:217], v[4:7]
	v_mfma_f32_16x16x32_bf16 v[0:3], v[174:177], v[214:217], v[0:3]
	v_mfma_f32_16x16x32_bf16 v[48:51], v[166:169], v[182:185], v[48:51]
	v_mfma_f32_16x16x32_bf16 v[52:55], v[174:177], v[182:185], v[52:55]
	s_setprio 0
	s_barrier
	s_add_i32 s51, 0, 0x18000
	s_add_i32 s52, 0, 0x1c000
	v_add_u32_e32 v68, s51, v157
	v_add_u32_e32 v154, s52, v157
	ds_read_b128 v[56:59], v68
	ds_read_b128 v[60:63], v68 offset:1024
	ds_read_b128 v[64:67], v68 offset:2048
	ds_read_b128 v[68:71], v68 offset:3072
	ds_read_b128 v[162:165], v154
	ds_read_b128 v[166:169], v154 offset:1024
	ds_read_b128 v[170:173], v154 offset:2048
	ds_read_b128 v[174:177], v154 offset:3072
	s_add_u32 s28, s28, 0x80000
	s_addc_u32 s29, s29, 0
	s_mov_b32 m0, s40
	v_lshl_add_u64 v[222:223], s[28:29], 0, v[148:149]
	ds_read_b128 v[178:181], v161 offset:32768
	ds_read_b128 v[182:185], v161 offset:33792
	ds_read_b128 v[186:189], v161 offset:34816
	ds_read_b128 v[190:193], v161 offset:35840
	ds_read_b128 v[194:197], v161 offset:36864
	ds_read_b128 v[198:201], v161 offset:37888
	ds_read_b128 v[202:205], v161 offset:38912
	ds_read_b128 v[214:217], v161 offset:39936
	global_load_lds_dwordx4 v[222:223], off
	v_lshl_add_u64 v[222:223], s[28:29], 0, v[146:147]
	s_mov_b32 m0, s41
	s_nop 0
	global_load_lds_dwordx4 v[222:223], off
	s_waitcnt vmcnt(8)
	s_waitcnt lgkmcnt(0)
	s_barrier
	s_setprio 1
	s_waitcnt lgkmcnt(0)
	v_mfma_f32_16x16x32_bf16 v[140:143], v[56:59], v[178:181], v[140:143]
	v_mfma_f32_16x16x32_bf16 v[136:139], v[64:67], v[178:181], v[136:139]
	v_mfma_f32_16x16x32_bf16 v[124:127], v[56:59], v[186:189], v[124:127]
	v_mfma_f32_16x16x32_bf16 v[120:123], v[64:67], v[186:189], v[120:123]
	v_mfma_f32_16x16x32_bf16 v[108:111], v[56:59], v[194:197], v[108:111]
	v_mfma_f32_16x16x32_bf16 v[104:107], v[64:67], v[194:197], v[104:107]
	v_mfma_f32_16x16x32_bf16 v[92:95], v[56:59], v[202:205], v[92:95]
	v_mfma_f32_16x16x32_bf16 v[88:91], v[64:67], v[202:205], v[88:91]
	v_mfma_f32_16x16x32_bf16 v[140:143], v[60:63], v[182:185], v[140:143]
	v_mfma_f32_16x16x32_bf16 v[136:139], v[68:71], v[182:185], v[136:139]
	v_mfma_f32_16x16x32_bf16 v[124:127], v[60:63], v[190:193], v[124:127]
	v_mfma_f32_16x16x32_bf16 v[120:123], v[68:71], v[190:193], v[120:123]
	v_mfma_f32_16x16x32_bf16 v[108:111], v[60:63], v[198:201], v[108:111]
	v_mfma_f32_16x16x32_bf16 v[104:107], v[68:71], v[198:201], v[104:107]
	v_mfma_f32_16x16x32_bf16 v[92:95], v[60:63], v[214:217], v[92:95]
	v_mfma_f32_16x16x32_bf16 v[88:91], v[68:71], v[214:217], v[88:91]
	s_setprio 0
	s_setprio 1
	v_mfma_f32_16x16x32_bf16 v[132:135], v[162:165], v[178:181], v[132:135]
	v_mfma_f32_16x16x32_bf16 v[128:131], v[170:173], v[178:181], v[128:131]
	v_mfma_f32_16x16x32_bf16 v[116:119], v[162:165], v[186:189], v[116:119]
	v_mfma_f32_16x16x32_bf16 v[112:115], v[170:173], v[186:189], v[112:115]
	v_mfma_f32_16x16x32_bf16 v[100:103], v[162:165], v[194:197], v[100:103]
	v_mfma_f32_16x16x32_bf16 v[96:99], v[170:173], v[194:197], v[96:99]
	v_mfma_f32_16x16x32_bf16 v[84:87], v[162:165], v[202:205], v[84:87]
	v_mfma_f32_16x16x32_bf16 v[80:83], v[170:173], v[202:205], v[80:83]
	v_mfma_f32_16x16x32_bf16 v[132:135], v[166:169], v[182:185], v[132:135]
	v_mfma_f32_16x16x32_bf16 v[128:131], v[174:177], v[182:185], v[128:131]
	v_mfma_f32_16x16x32_bf16 v[116:119], v[166:169], v[190:193], v[116:119]
	v_mfma_f32_16x16x32_bf16 v[112:115], v[174:177], v[190:193], v[112:115]
	v_mfma_f32_16x16x32_bf16 v[100:103], v[166:169], v[198:201], v[100:103]
	v_mfma_f32_16x16x32_bf16 v[96:99], v[174:177], v[198:201], v[96:99]
	v_mfma_f32_16x16x32_bf16 v[84:87], v[166:169], v[214:217], v[84:87]
	v_mfma_f32_16x16x32_bf16 v[80:83], v[174:177], v[214:217], v[80:83]
	s_setprio 0
	s_barrier
; #define PG8_STAGE(bufoff, gbase, voff) do { _Pragma("unroll") for (int _i = 0; _i < 2; ++_i) \
;         __builtin_amdgcn_global_load_lds((const unsigned*)((const char*)(gbase) + (voff)[_i]), (PG8_LAS unsigned*)(lds + (bufoff) + ldsw + _i * 8192), 16, 0, 0); } while (0)
; #define PG8_LDA(dst, b, h) do { _Pragma("unroll") for (int m = 0; m < 4; ++m) _Pragma("unroll") for (int k = 0; k < 2; ++k) dst[m][k] = *(const PG8_LAS bf16x8*)(lds + PG8_SA(b, h) + aoff + m * 2048 + k * 1024); } while (0)
; #define PG8_MMA(ai, bj, At, Bt) do { __builtin_amdgcn_s_setprio(1); _Pragma("unroll") for (int m = 0; m < 4; ++m) _Pragma("unroll") for (int n = 0; n < 2; ++n) _Pragma("unroll") for (int k = 0; k < 2; ++k) \
;         acc[ai][bj][m][n] = __builtin_amdgcn_mfma_f32_16x16x32_bf16(Bt[n][k], At[m][k], acc[ai][bj][m][n], 0, 0, 0); __builtin_amdgcn_s_setprio(0); } while (0)
; #define PG8_WAIT_V(n) asm volatile("s_waitcnt vmcnt(" #n ")" ::: "memory")
; #define PG8_WAIT_L(n) asm volatile("s_waitcnt lgkmcnt(" #n ")" ::: "memory")
; #define PG8_BAR __builtin_amdgcn_s_barrier()
; #define PG8_SCHED __builtin_amdgcn_sched_barrier(0)
; template <class Epi, class Sched, bool ALIGN_EPI = false, bool SP2 = false>
; __device__ __forceinline__ void gemm_phase(PG8_LAS unsigned char* lds, const Gemm g, const Sched& S, const Epi& E, const int tid) {
;     ...
;             PG8_LDA(At, 1, 1); PG8_STAGE(PG8_SB(1, 0), b3, voffB); PG8_STAGE(PG8_SB(1, 1), b3 + hstep, voffB); PG8_STAGE(PG8_SA(1, 0), a3, voffA);
;             PG8_WAIT_V(8); PG8_WAIT_L(0); PG8_BAR; PG8_MMA(1, 0, At, B0); PG8_MMA(1, 1, At, B1); PG8_BAR; PG8_SCHED;
;     __device__ __forceinline__ void operator()(const f32x4 (&acc)[2][2][4][2], const Unit& un, int wr, int wc, int fr, int fq) const {
;         const int rbase = un.pm * 256 + wr * 64 + fr, cw = un.pn * 256 + wc * 32 + 8 * fq;
;         const int slot = un.pm < (NLAT / 256) ? (un.pm >> 5) : 4; const float* sw = shw + (size_t)slot * DFF;
;         f32x4 s0[2], s1[2]; float rr[2][4];
; #pragma unroll
;         for (int bj = 0; bj < 2; ++bj) { s0[bj] = *(const f32x4*)(sw + cw + bj * 128); s1[bj] = *(const f32x4*)(sw + cw + bj * 128 + 4); }
; #pragma unroll
;         for (int ai = 0; ai < 2; ++ai)
; #pragma unroll
;             for (int m = 0; m < 4; ++m) rr[ai][m] = rs[rbase + ai * 128 + m * 16];
	s_add_i32 s28, s51, s38
	v_lshl_add_u64 v[206:207], v[206:207], 0, s[2:3]
	s_mov_b32 m0, s28
	ds_read_b128 v[178:181], v161 offset:49152
	ds_read_b128 v[182:185], v161 offset:50176
	ds_read_b128 v[186:189], v161 offset:51200
	ds_read_b128 v[190:193], v161 offset:52224
	ds_read_b128 v[194:197], v161 offset:53248
	ds_read_b128 v[198:201], v161 offset:54272
	ds_read_b128 v[202:205], v161 offset:55296
	ds_read_b128 v[214:217], v161 offset:56320
	global_load_lds_dwordx4 v[206:207], off
	s_add_i32 m0, s28, 0x2000
	s_add_u32 s26, s26, 0x80080
	v_lshl_add_u64 v[206:207], v[210:211], 0, s[2:3]
	s_addc_u32 s27, s27, 0
	s_add_i32 s28, s52, s38
	global_load_lds_dwordx4 v[206:207], off
	v_lshl_add_u64 v[206:207], s[26:27], 0, v[208:209]
	s_mov_b32 m0, s28
	s_nop 0
	global_load_lds_dwordx4 v[206:207], off
	v_lshl_add_u64 v[206:207], s[26:27], 0, v[144:145]
	s_add_i32 m0, s28, 0x2000
	s_nop 0
	global_load_lds_dwordx4 v[206:207], off
	v_lshl_add_u64 v[206:207], v[218:219], 0, s[2:3]
	s_mov_b32 m0, s44
	s_nop 0
	global_load_lds_dwordx4 v[206:207], off
	v_lshl_add_u64 v[206:207], v[220:221], 0, s[2:3]
	s_mov_b32 m0, s45
	s_nop 0
	global_load_lds_dwordx4 v[206:207], off
	s_waitcnt vmcnt(8)
	s_waitcnt lgkmcnt(0)
	s_barrier
	s_setprio 1
	s_waitcnt lgkmcnt(0)
	v_mfma_f32_16x16x32_bf16 v[76:79], v[56:59], v[178:181], v[76:79]
	v_mfma_f32_16x16x32_bf16 v[72:75], v[64:67], v[178:181], v[72:75]
	v_mfma_f32_16x16x32_bf16 v[44:47], v[56:59], v[186:189], v[44:47]
	v_mfma_f32_16x16x32_bf16 v[40:43], v[64:67], v[186:189], v[40:43]
	v_mfma_f32_16x16x32_bf16 v[28:31], v[56:59], v[194:197], v[28:31]
	v_mfma_f32_16x16x32_bf16 v[24:27], v[64:67], v[194:197], v[24:27]
	v_mfma_f32_16x16x32_bf16 v[12:15], v[56:59], v[202:205], v[12:15]
	v_mfma_f32_16x16x32_bf16 v[8:11], v[64:67], v[202:205], v[8:11]
	v_mfma_f32_16x16x32_bf16 v[76:79], v[60:63], v[182:185], v[76:79]
	v_mfma_f32_16x16x32_bf16 v[72:75], v[68:71], v[182:185], v[72:75]
	v_mfma_f32_16x16x32_bf16 v[44:47], v[60:63], v[190:193], v[44:47]
	v_mfma_f32_16x16x32_bf16 v[40:43], v[68:71], v[190:193], v[40:43]
	v_mfma_f32_16x16x32_bf16 v[28:31], v[60:63], v[198:201], v[28:31]
	v_mfma_f32_16x16x32_bf16 v[24:27], v[68:71], v[198:201], v[24:27]
	v_mfma_f32_16x16x32_bf16 v[12:15], v[60:63], v[214:217], v[12:15]
	v_mfma_f32_16x16x32_bf16 v[8:11], v[68:71], v[214:217], v[8:11]
	s_setprio 0
	s_setprio 1
	v_mfma_f32_16x16x32_bf16 v[48:51], v[162:165], v[178:181], v[48:51]
	v_mfma_f32_16x16x32_bf16 v[60:63], v[166:169], v[182:185], v[48:51]
	v_mfma_f32_16x16x32_bf16 v[48:51], v[170:173], v[178:181], v[52:55]
	v_mfma_f32_16x16x32_bf16 v[36:39], v[162:165], v[186:189], v[36:39]
	v_mfma_f32_16x16x32_bf16 v[32:35], v[170:173], v[186:189], v[32:35]
	v_mfma_f32_16x16x32_bf16 v[20:23], v[162:165], v[194:197], v[20:23]
	v_mfma_f32_16x16x32_bf16 v[16:19], v[170:173], v[194:197], v[16:19]
	v_mfma_f32_16x16x32_bf16 v[4:7], v[162:165], v[202:205], v[4:7]
	v_mfma_f32_16x16x32_bf16 v[0:3], v[170:173], v[202:205], v[0:3]
	v_mfma_f32_16x16x32_bf16 v[56:59], v[174:177], v[182:185], v[48:51]
	v_mfma_f32_16x16x32_bf16 v[36:39], v[166:169], v[190:193], v[36:39]
	v_mfma_f32_16x16x32_bf16 v[32:35], v[174:177], v[190:193], v[32:35]
	v_mfma_f32_16x16x32_bf16 v[20:23], v[166:169], v[198:201], v[20:23]
	v_mfma_f32_16x16x32_bf16 v[16:19], v[174:177], v[198:201], v[16:19]
	v_mfma_f32_16x16x32_bf16 v[4:7], v[166:169], v[214:217], v[4:7]
	v_mfma_f32_16x16x32_bf16 v[0:3], v[174:177], v[214:217], v[0:3]
	s_setprio 0
	s_barrier
	s_add_i32 s50, s50, 2
	s_add_u32 s24, s24, 0x100
	s_addc_u32 s25, s25, 0
	s_add_u32 s48, s48, 0x100
	s_addc_u32 s49, s49, 0
	s_cmp_gt_u32 s50, 29
	s_cbranch_scc0 .LBB0_1047
	s_ashr_i32 s24, s20, 5
	s_ashr_i32 s25, s24, 31
	s_lshl_b64 s[24:25], s[24:25], 13
	s_cmpk_lt_i32 s20, 0x80
	s_cselect_b32 s25, s25, 0
	s_cselect_b32 s24, s24, 0x8000
	s_lshl_b64 s[24:25], s[24:25], 2
	v_lshl_or_b32 v176, s22, 8, v159
	s_add_u32 s24, s42, s24
	v_lshl_add_u32 v178, s20, 8, v155
	s_addc_u32 s25, s43, s25
	v_ashrrev_i32_e32 v177, 31, v176
	v_ashrrev_i32_e32 v179, 31, v178
	v_lshl_add_u64 v[52:53], v[176:177], 2, s[24:25]
	v_lshl_add_u64 v[180:181], v[178:179], 2, s[6:7]
	global_load_dwordx4 v[64:67], v[52:53], off offset:16
	global_load_dwordx4 v[68:71], v[52:53], off
	global_load_dwordx4 v[48:51], v[52:53], off offset:528
	s_nop 0
	global_load_dwordx4 v[52:55], v[52:53], off offset:512
	v_or_b32_e32 v172, 16, v178
	global_load_dword v174, v[180:181], off
	v_ashrrev_i32_e32 v173, 31, v172
	v_lshl_add_u64 v[162:163], v[172:173], 2, s[6:7]
	global_load_dword v170, v[162:163], off
	v_or_b32_e32 v168, 32, v178
	v_ashrrev_i32_e32 v169, 31, v168
	v_lshl_add_u64 v[162:163], v[168:169], 2, s[6:7]
	global_load_dword v166, v[162:163], off
	v_or_b32_e32 v164, 48, v178
	v_lshlrev_b64 v[178:179], 14, v[178:179]
	v_ashrrev_i32_e32 v165, 31, v164
	v_lshl_add_u64 v[162:163], v[164:165], 2, s[6:7]
	global_load_dword v162, v[162:163], off
	s_nop 0
	global_load_dword v160, v[180:181], off offset:512
	global_load_dword v158, v[180:181], off offset:576
	global_load_dword v156, v[180:181], off offset:640
	global_load_dword v154, v[180:181], off offset:704
	s_and_b64 vcc, exec, s[8:9]
	s_cbranch_vccz .LBB0_1050
	s_barrier

; #define PG8_STAGE(bufoff, gbase, voff) do { _Pragma("unroll") for (int _i = 0; _i < 2; ++_i) \
;         __builtin_amdgcn_global_load_lds((const unsigned*)((const char*)(gbase) + (voff)[_i]), (PG8_LAS unsigned*)(lds + (bufoff) + ldsw + _i * 8192), 16, 0, 0); } while (0)
; #define PG8_LDA(dst, b, h) do { _Pragma("unroll") for (int m = 0; m < 4; ++m) _Pragma("unroll") for (int k = 0; k < 2; ++k) dst[m][k] = *(const PG8_LAS bf16x8*)(lds + PG8_SA(b, h) + aoff + m * 2048 + k * 1024); } while (0)
; #define PG8_LDB(dst, b, h) do { _Pragma("unroll") for (int n = 0; n < 2; ++n) _Pragma("unroll") for (int k = 0; k < 2; ++k) dst[n][k] = *(const PG8_LAS bf16x8*)(lds + PG8_SB(b, h) + boff + n * 2048 + k * 1024); } while (0)
; #define PG8_MMA(ai, bj, At, Bt) do { __builtin_amdgcn_s_setprio(1); _Pragma("unroll") for (int m = 0; m < 4; ++m) _Pragma("unroll") for (int n = 0; n < 2; ++n) _Pragma("unroll") for (int k = 0; k < 2; ++k) \
;         acc[ai][bj][m][n] = __builtin_amdgcn_mfma_f32_16x16x32_bf16(Bt[n][k], At[m][k], acc[ai][bj][m][n], 0, 0, 0); __builtin_amdgcn_s_setprio(0); } while (0)
; #define PG8_WAIT_V(n) asm volatile("s_waitcnt vmcnt(" #n ")" ::: "memory")
; #define PG8_WAIT_L(n) asm volatile("s_waitcnt lgkmcnt(" #n ")" ::: "memory")
; #define PG8_BAR __builtin_amdgcn_s_barrier()
; #define PG8_SCHED __builtin_amdgcn_sched_barrier(0)
; template <class Epi, class Sched, bool ALIGN_EPI = false, bool SP2 = false>
; __device__ __forceinline__ void gemm_phase(PG8_LAS unsigned char* lds, const Gemm g, const Sched& S, const Epi& E, const int tid) {
;     ...
;             PG8_LDB(B0, 0, 0); PG8_LDB(B1, 0, 1); PG8_SCHED; PG8_LDA(At, 0, 0); PG8_STAGE(PG8_SA(1, 1), a1 + hstep, voffA);
;             PG8_WAIT_V(8); PG8_WAIT_L(0); PG8_BAR; PG8_MMA(0, 0, At, B0); PG8_MMA(0, 1, At, B1); PG8_BAR; PG8_SCHED;
;             PG8_LDA(At, 0, 1); PG8_STAGE(PG8_SB(0, 0), b2, voffB); PG8_STAGE(PG8_SB(0, 1), b2 + hstep, voffB); PG8_STAGE(PG8_SA(0, 0), a2, voffA);
.LBB0_1479:
	s_add_u32 s30, s28, 0xfff80080
	s_addc_u32 s31, s29, -1
	s_add_i32 s57, 0, 0x10000
	v_add_u32_e32 v124, s57, v157
	v_add_u32_e32 v154, s33, v157
	ds_read_b128 v[112:115], v124
	ds_read_b128 v[116:119], v124 offset:1024
	ds_read_b128 v[120:123], v124 offset:2048
	ds_read_b128 v[124:127], v124 offset:3072
	ds_read_b128 v[162:165], v154
	ds_read_b128 v[166:169], v154 offset:1024
	ds_read_b128 v[170:173], v154 offset:2048
	ds_read_b128 v[174:177], v154 offset:3072
	s_cmp_eq_u32 s56, 28
	s_cselect_b32 s35, s19, s31
	s_cselect_b32 s34, s25, s30
	s_cselect_b32 s31, s17, s55
	s_cselect_b32 s30, s53, s54
	v_lshl_add_u64 v[206:207], s[28:29], 0, v[150:151]
	s_add_i32 m0, s27, 0xc000
	ds_read_b128 v[178:181], v161
	ds_read_b128 v[182:185], v161 offset:1024
	ds_read_b128 v[186:189], v161 offset:2048
	ds_read_b128 v[190:193], v161 offset:3072
	ds_read_b128 v[194:197], v161 offset:4096
	ds_read_b128 v[198:201], v161 offset:5120
	ds_read_b128 v[202:205], v161 offset:6144
	ds_read_b128 v[214:217], v161 offset:7168
	global_load_lds_dwordx4 v[206:207], off
	v_lshl_add_u64 v[206:207], s[28:29], 0, v[152:153]
	s_add_i32 m0, s27, 0xe000
	s_nop 0
	global_load_lds_dwordx4 v[206:207], off
	s_waitcnt vmcnt(8)
	s_waitcnt lgkmcnt(0)
	s_barrier
	s_setprio 1
	s_waitcnt lgkmcnt(0)
	v_mfma_f32_16x16x32_bf16 v[140:143], v[112:115], v[178:181], v[140:143]
	v_mfma_f32_16x16x32_bf16 v[136:139], v[120:123], v[178:181], v[136:139]
	v_mfma_f32_16x16x32_bf16 v[108:111], v[112:115], v[186:189], v[108:111]
	v_mfma_f32_16x16x32_bf16 v[104:107], v[120:123], v[186:189], v[104:107]
	v_mfma_f32_16x16x32_bf16 v[92:95], v[112:115], v[194:197], v[92:95]
	v_mfma_f32_16x16x32_bf16 v[88:91], v[120:123], v[194:197], v[88:91]
	v_mfma_f32_16x16x32_bf16 v[76:79], v[112:115], v[202:205], v[76:79]
	v_mfma_f32_16x16x32_bf16 v[72:75], v[120:123], v[202:205], v[72:75]
	v_mfma_f32_16x16x32_bf16 v[140:143], v[116:119], v[182:185], v[140:143]
	v_mfma_f32_16x16x32_bf16 v[136:139], v[124:127], v[182:185], v[136:139]
	v_mfma_f32_16x16x32_bf16 v[108:111], v[116:119], v[190:193], v[108:111]
	v_mfma_f32_16x16x32_bf16 v[104:107], v[124:127], v[190:193], v[104:107]
	v_mfma_f32_16x16x32_bf16 v[92:95], v[116:119], v[198:201], v[92:95]
	v_mfma_f32_16x16x32_bf16 v[88:91], v[124:127], v[198:201], v[88:91]
	v_mfma_f32_16x16x32_bf16 v[76:79], v[116:119], v[214:217], v[76:79]
	v_mfma_f32_16x16x32_bf16 v[72:75], v[124:127], v[214:217], v[72:75]
	s_setprio 0
	s_setprio 1
	v_mfma_f32_16x16x32_bf16 v[132:135], v[162:165], v[178:181], v[132:135]
	v_mfma_f32_16x16x32_bf16 v[128:131], v[170:173], v[178:181], v[128:131]
	v_mfma_f32_16x16x32_bf16 v[100:103], v[162:165], v[186:189], v[100:103]
	v_mfma_f32_16x16x32_bf16 v[96:99], v[170:173], v[186:189], v[96:99]
	v_mfma_f32_16x16x32_bf16 v[84:87], v[162:165], v[194:197], v[84:87]
	v_mfma_f32_16x16x32_bf16 v[80:83], v[170:173], v[194:197], v[80:83]
	v_mfma_f32_16x16x32_bf16 v[68:71], v[162:165], v[202:205], v[68:71]
	v_mfma_f32_16x16x32_bf16 v[64:67], v[170:173], v[202:205], v[64:67]
	v_mfma_f32_16x16x32_bf16 v[132:135], v[166:169], v[182:185], v[132:135]
	v_mfma_f32_16x16x32_bf16 v[128:131], v[174:177], v[182:185], v[128:131]
	v_mfma_f32_16x16x32_bf16 v[100:103], v[166:169], v[190:193], v[100:103]
	v_mfma_f32_16x16x32_bf16 v[96:99], v[174:177], v[190:193], v[96:99]
	v_mfma_f32_16x16x32_bf16 v[84:87], v[166:169], v[198:201], v[84:87]
	v_mfma_f32_16x16x32_bf16 v[80:83], v[174:177], v[198:201], v[80:83]
	v_mfma_f32_16x16x32_bf16 v[68:71], v[166:169], v[214:217], v[68:71]
	v_mfma_f32_16x16x32_bf16 v[64:67], v[174:177], v[214:217], v[64:67]
	s_setprio 0
	s_barrier
	s_add_i32 s57, s57, s42
	v_lshl_add_u64 v[206:207], s[30:31], 0, v[208:209]
	s_mov_b32 m0, s57
	ds_read_b128 v[178:181], v161 offset:16384
	ds_read_b128 v[182:185], v161 offset:17408
	ds_read_b128 v[186:189], v161 offset:18432
	ds_read_b128 v[190:193], v161 offset:19456
	ds_read_b128 v[194:197], v161 offset:20480
	ds_read_b128 v[198:201], v161 offset:21504
	ds_read_b128 v[202:205], v161 offset:22528
	ds_read_b128 v[214:217], v161 offset:23552
	global_load_lds_dwordx4 v[206:207], off
	s_add_i32 m0, s57, 0x2000
	s_add_u32 s58, s30, 0x80000
	v_lshl_add_u64 v[210:211], s[30:31], 0, v[144:145]
	s_addc_u32 s59, s31, 0
	s_add_i32 s57, s33, s42
	global_load_lds_dwordx4 v[210:211], off
	v_lshl_add_u64 v[212:213], s[58:59], 0, v[208:209]
	s_mov_b32 m0, s57
	v_lshl_add_u64 v[218:219], s[34:35], 0, v[146:147]
	global_load_lds_dwordx4 v[212:213], off
	v_lshl_add_u64 v[212:213], s[58:59], 0, v[144:145]
	s_add_i32 m0, s57, 0x2000
	s_nop 0
	global_load_lds_dwordx4 v[212:213], off
	v_lshl_add_u64 v[212:213], s[34:35], 0, v[148:149]
	s_mov_b32 m0, s27
	s_nop 0
	global_load_lds_dwordx4 v[212:213], off
	s_mov_b32 m0, s44
	s_nop 0
	global_load_lds_dwordx4 v[218:219], off
	s_waitcnt vmcnt(8)
	s_waitcnt lgkmcnt(0)
	s_barrier
; #define PG8_STAGE(bufoff, gbase, voff) do { _Pragma("unroll") for (int _i = 0; _i < 2; ++_i) \
;         __builtin_amdgcn_global_load_lds((const unsigned*)((const char*)(gbase) + (voff)[_i]), (PG8_LAS unsigned*)(lds + (bufoff) + ldsw + _i * 8192), 16, 0, 0); } while (0)
; #define PG8_LDA(dst, b, h) do { _Pragma("unroll") for (int m = 0; m < 4; ++m) _Pragma("unroll") for (int k = 0; k < 2; ++k) dst[m][k] = *(const PG8_LAS bf16x8*)(lds + PG8_SA(b, h) + aoff + m * 2048 + k * 1024); } while (0)
; #define PG8_LDB(dst, b, h) do { _Pragma("unroll") for (int n = 0; n < 2; ++n) _Pragma("unroll") for (int k = 0; k < 2; ++k) dst[n][k] = *(const PG8_LAS bf16x8*)(lds + PG8_SB(b, h) + boff + n * 2048 + k * 1024); } while (0)
; #define PG8_MMA(ai, bj, At, Bt) do { __builtin_amdgcn_s_setprio(1); _Pragma("unroll") for (int m = 0; m < 4; ++m) _Pragma("unroll") for (int n = 0; n < 2; ++n) _Pragma("unroll") for (int k = 0; k < 2; ++k) \
;         acc[ai][bj][m][n] = __builtin_amdgcn_mfma_f32_16x16x32_bf16(Bt[n][k], At[m][k], acc[ai][bj][m][n], 0, 0, 0); __builtin_amdgcn_s_setprio(0); } while (0)
; #define PG8_WAIT_V(n) asm volatile("s_waitcnt vmcnt(" #n ")" ::: "memory")
; #define PG8_WAIT_L(n) asm volatile("s_waitcnt lgkmcnt(" #n ")" ::: "memory")
; #define PG8_BAR __builtin_amdgcn_s_barrier()
; #define PG8_SCHED __builtin_amdgcn_sched_barrier(0)
; template <class Epi, class Sched, bool ALIGN_EPI = false, bool SP2 = false>
; __device__ __forceinline__ void gemm_phase(PG8_LAS unsigned char* lds, const Gemm g, const Sched& S, const Epi& E, const int tid) {
;     ...
;             PG8_WAIT_V(8); PG8_WAIT_L(0); PG8_BAR; PG8_MMA(1, 0, At, B0); PG8_MMA(1, 1, At, B1); PG8_BAR; PG8_SCHED;
;             PG8_LDB(B0, 1, 0); PG8_LDB(B1, 1, 1); PG8_SCHED; PG8_LDA(At, 1, 0); PG8_STAGE(PG8_SA(0, 1), a2 + hstep, voffA);
;             PG8_WAIT_V(8); PG8_WAIT_L(0); PG8_BAR; PG8_MMA(0, 0, At, B0); PG8_MMA(0, 1, At, B1); PG8_BAR; PG8_SCHED;
	s_setprio 1
	s_waitcnt lgkmcnt(0)
	v_mfma_f32_16x16x32_bf16 v[60:63], v[112:115], v[178:181], v[60:63]
	v_mfma_f32_16x16x32_bf16 v[56:59], v[120:123], v[178:181], v[56:59]
	v_mfma_f32_16x16x32_bf16 v[44:47], v[112:115], v[186:189], v[44:47]
	v_mfma_f32_16x16x32_bf16 v[40:43], v[120:123], v[186:189], v[40:43]
	v_mfma_f32_16x16x32_bf16 v[28:31], v[112:115], v[194:197], v[28:31]
	v_mfma_f32_16x16x32_bf16 v[24:27], v[120:123], v[194:197], v[24:27]
	v_mfma_f32_16x16x32_bf16 v[12:15], v[112:115], v[202:205], v[12:15]
	v_mfma_f32_16x16x32_bf16 v[8:11], v[120:123], v[202:205], v[8:11]
	v_mfma_f32_16x16x32_bf16 v[60:63], v[116:119], v[182:185], v[60:63]
	v_mfma_f32_16x16x32_bf16 v[56:59], v[124:127], v[182:185], v[56:59]
	v_mfma_f32_16x16x32_bf16 v[44:47], v[116:119], v[190:193], v[44:47]
	v_mfma_f32_16x16x32_bf16 v[40:43], v[124:127], v[190:193], v[40:43]
	v_mfma_f32_16x16x32_bf16 v[28:31], v[116:119], v[198:201], v[28:31]
	v_mfma_f32_16x16x32_bf16 v[24:27], v[124:127], v[198:201], v[24:27]
	v_mfma_f32_16x16x32_bf16 v[12:15], v[116:119], v[214:217], v[12:15]
	v_mfma_f32_16x16x32_bf16 v[8:11], v[124:127], v[214:217], v[8:11]
	s_setprio 0
	s_setprio 1
	v_mfma_f32_16x16x32_bf16 v[52:55], v[162:165], v[178:181], v[52:55]
	v_mfma_f32_16x16x32_bf16 v[48:51], v[170:173], v[178:181], v[48:51]
	v_mfma_f32_16x16x32_bf16 v[36:39], v[162:165], v[186:189], v[36:39]
	v_mfma_f32_16x16x32_bf16 v[32:35], v[170:173], v[186:189], v[32:35]
	v_mfma_f32_16x16x32_bf16 v[20:23], v[162:165], v[194:197], v[20:23]
	v_mfma_f32_16x16x32_bf16 v[16:19], v[170:173], v[194:197], v[16:19]
	v_mfma_f32_16x16x32_bf16 v[4:7], v[162:165], v[202:205], v[4:7]
	v_mfma_f32_16x16x32_bf16 v[0:3], v[170:173], v[202:205], v[0:3]
	v_mfma_f32_16x16x32_bf16 v[52:55], v[166:169], v[182:185], v[52:55]
	v_mfma_f32_16x16x32_bf16 v[48:51], v[174:177], v[182:185], v[48:51]
	v_mfma_f32_16x16x32_bf16 v[36:39], v[166:169], v[190:193], v[36:39]
	v_mfma_f32_16x16x32_bf16 v[32:35], v[174:177], v[190:193], v[32:35]
	v_mfma_f32_16x16x32_bf16 v[20:23], v[166:169], v[198:201], v[20:23]
	v_mfma_f32_16x16x32_bf16 v[16:19], v[174:177], v[198:201], v[16:19]
	v_mfma_f32_16x16x32_bf16 v[4:7], v[166:169], v[214:217], v[4:7]
	v_mfma_f32_16x16x32_bf16 v[0:3], v[174:177], v[214:217], v[0:3]
	s_setprio 0
	s_barrier
	s_add_i32 s57, 0, 0x18000
	s_add_i32 s58, 0, 0x1c000
	v_add_u32_e32 v124, s57, v157
	v_add_u32_e32 v154, s58, v157
	ds_read_b128 v[112:115], v124
	ds_read_b128 v[116:119], v124 offset:1024
	ds_read_b128 v[120:123], v124 offset:2048
	ds_read_b128 v[124:127], v124 offset:3072
	ds_read_b128 v[162:165], v154
	ds_read_b128 v[166:169], v154 offset:1024
	ds_read_b128 v[170:173], v154 offset:2048
	ds_read_b128 v[174:177], v154 offset:3072
	s_add_u32 s34, s34, 0x80000
	s_addc_u32 s35, s35, 0
	s_mov_b32 m0, s45
	v_lshl_add_u64 v[220:221], s[34:35], 0, v[148:149]
	ds_read_b128 v[178:181], v161 offset:32768
	ds_read_b128 v[182:185], v161 offset:33792
	ds_read_b128 v[186:189], v161 offset:34816
	ds_read_b128 v[190:193], v161 offset:35840
	ds_read_b128 v[194:197], v161 offset:36864
	ds_read_b128 v[198:201], v161 offset:37888
	ds_read_b128 v[202:205], v161 offset:38912
	ds_read_b128 v[214:217], v161 offset:39936
	global_load_lds_dwordx4 v[220:221], off
	v_lshl_add_u64 v[220:221], s[34:35], 0, v[146:147]
	s_mov_b32 m0, s46
	s_nop 0
	global_load_lds_dwordx4 v[220:221], off
	s_waitcnt vmcnt(8)
	s_waitcnt lgkmcnt(0)
	s_barrier
	s_setprio 1
	s_waitcnt lgkmcnt(0)
	v_mfma_f32_16x16x32_bf16 v[140:143], v[112:115], v[178:181], v[140:143]
	v_mfma_f32_16x16x32_bf16 v[136:139], v[120:123], v[178:181], v[136:139]
	v_mfma_f32_16x16x32_bf16 v[108:111], v[112:115], v[186:189], v[108:111]
	v_mfma_f32_16x16x32_bf16 v[104:107], v[120:123], v[186:189], v[104:107]
	v_mfma_f32_16x16x32_bf16 v[92:95], v[112:115], v[194:197], v[92:95]
	v_mfma_f32_16x16x32_bf16 v[88:91], v[120:123], v[194:197], v[88:91]
	v_mfma_f32_16x16x32_bf16 v[76:79], v[112:115], v[202:205], v[76:79]
	v_mfma_f32_16x16x32_bf16 v[72:75], v[120:123], v[202:205], v[72:75]
	v_mfma_f32_16x16x32_bf16 v[140:143], v[116:119], v[182:185], v[140:143]
	v_mfma_f32_16x16x32_bf16 v[136:139], v[124:127], v[182:185], v[136:139]
	v_mfma_f32_16x16x32_bf16 v[108:111], v[116:119], v[190:193], v[108:111]
	v_mfma_f32_16x16x32_bf16 v[104:107], v[124:127], v[190:193], v[104:107]
	v_mfma_f32_16x16x32_bf16 v[92:95], v[116:119], v[198:201], v[92:95]
	v_mfma_f32_16x16x32_bf16 v[88:91], v[124:127], v[198:201], v[88:91]
	v_mfma_f32_16x16x32_bf16 v[76:79], v[116:119], v[214:217], v[76:79]
	v_mfma_f32_16x16x32_bf16 v[72:75], v[124:127], v[214:217], v[72:75]
	s_setprio 0
	s_setprio 1
	v_mfma_f32_16x16x32_bf16 v[132:135], v[162:165], v[178:181], v[132:135]
	v_mfma_f32_16x16x32_bf16 v[128:131], v[170:173], v[178:181], v[128:131]
	v_mfma_f32_16x16x32_bf16 v[100:103], v[162:165], v[186:189], v[100:103]
	v_mfma_f32_16x16x32_bf16 v[96:99], v[170:173], v[186:189], v[96:99]
	v_mfma_f32_16x16x32_bf16 v[84:87], v[162:165], v[194:197], v[84:87]
	v_mfma_f32_16x16x32_bf16 v[80:83], v[170:173], v[194:197], v[80:83]
	v_mfma_f32_16x16x32_bf16 v[68:71], v[162:165], v[202:205], v[68:71]
	v_mfma_f32_16x16x32_bf16 v[64:67], v[170:173], v[202:205], v[64:67]
	v_mfma_f32_16x16x32_bf16 v[132:135], v[166:169], v[182:185], v[132:135]
	v_mfma_f32_16x16x32_bf16 v[128:131], v[174:177], v[182:185], v[128:131]
	v_mfma_f32_16x16x32_bf16 v[100:103], v[166:169], v[190:193], v[100:103]
	v_mfma_f32_16x16x32_bf16 v[96:99], v[174:177], v[190:193], v[96:99]
	v_mfma_f32_16x16x32_bf16 v[84:87], v[166:169], v[198:201], v[84:87]
	v_mfma_f32_16x16x32_bf16 v[80:83], v[174:177], v[198:201], v[80:83]
	v_mfma_f32_16x16x32_bf16 v[68:71], v[166:169], v[214:217], v[68:71]
	v_mfma_f32_16x16x32_bf16 v[64:67], v[174:177], v[214:217], v[64:67]
	s_setprio 0
	s_barrier
; #define PG8_STAGE(bufoff, gbase, voff) do { _Pragma("unroll") for (int _i = 0; _i < 2; ++_i) \
;         __builtin_amdgcn_global_load_lds((const unsigned*)((const char*)(gbase) + (voff)[_i]), (PG8_LAS unsigned*)(lds + (bufoff) + ldsw + _i * 8192), 16, 0, 0); } while (0)
; #define PG8_LDA(dst, b, h) do { _Pragma("unroll") for (int m = 0; m < 4; ++m) _Pragma("unroll") for (int k = 0; k < 2; ++k) dst[m][k] = *(const PG8_LAS bf16x8*)(lds + PG8_SA(b, h) + aoff + m * 2048 + k * 1024); } while (0)
; #define PG8_MMA(ai, bj, At, Bt) do { __builtin_amdgcn_s_setprio(1); _Pragma("unroll") for (int m = 0; m < 4; ++m) _Pragma("unroll") for (int n = 0; n < 2; ++n) _Pragma("unroll") for (int k = 0; k < 2; ++k) \
;         acc[ai][bj][m][n] = __builtin_amdgcn_mfma_f32_16x16x32_bf16(Bt[n][k], At[m][k], acc[ai][bj][m][n], 0, 0, 0); __builtin_amdgcn_s_setprio(0); } while (0)
; #define PG8_WAIT_V(n) asm volatile("s_waitcnt vmcnt(" #n ")" ::: "memory")
; #define PG8_WAIT_L(n) asm volatile("s_waitcnt lgkmcnt(" #n ")" ::: "memory")
; #define PG8_BAR __builtin_amdgcn_s_barrier()
; #define PG8_SCHED __builtin_amdgcn_sched_barrier(0)
; template <class Epi, class Sched, bool ALIGN_EPI = false, bool SP2 = false>
; __device__ __forceinline__ void gemm_phase(PG8_LAS unsigned char* lds, const Gemm g, const Sched& S, const Epi& E, const int tid) {
;     ...
;             PG8_LDA(At, 1, 1); PG8_STAGE(PG8_SB(1, 0), b3, voffB); PG8_STAGE(PG8_SB(1, 1), b3 + hstep, voffB); PG8_STAGE(PG8_SA(1, 0), a3, voffA);
;             PG8_WAIT_V(8); PG8_WAIT_L(0); PG8_BAR; PG8_MMA(1, 0, At, B0); PG8_MMA(1, 1, At, B1); PG8_BAR; PG8_SCHED;
;     __device__ __forceinline__ void operator()(const f32x4 (&acc)[2][2][4][2], const Unit& un, int wr, int wc, int fr, int fq) const {
;         const int rbase = un.pm * 256 + wr * 64 + fr, cw = un.pn * 256 + wc * 32 + 8 * fq;
;         const int slot = un.pm < (NLAT / 256) ? (un.pm >> 5) : 4; const float* sw = shw + (size_t)slot * DFF;
;         f32x4 s0[2], s1[2]; float rr[2][4];
; #pragma unroll
;         for (int bj = 0; bj < 2; ++bj) { s0[bj] = *(const f32x4*)(sw + cw + bj * 128); s1[bj] = *(const f32x4*)(sw + cw + bj * 128 + 4); }
; #pragma unroll
;         for (int ai = 0; ai < 2; ++ai)
; #pragma unroll
;             for (int m = 0; m < 4; ++m) rr[ai][m] = rs[rbase + ai * 128 + m * 16];
	s_add_i32 s34, s57, s42
	v_lshl_add_u64 v[206:207], v[206:207], 0, s[2:3]
	s_mov_b32 m0, s34
	ds_read_b128 v[178:181], v161 offset:49152
	ds_read_b128 v[182:185], v161 offset:50176
	ds_read_b128 v[186:189], v161 offset:51200
	ds_read_b128 v[190:193], v161 offset:52224
	ds_read_b128 v[194:197], v161 offset:53248
	ds_read_b128 v[198:201], v161 offset:54272
	ds_read_b128 v[202:205], v161 offset:55296
	ds_read_b128 v[214:217], v161 offset:56320
	global_load_lds_dwordx4 v[206:207], off
	s_add_i32 m0, s34, 0x2000
	s_add_u32 s30, s30, 0x80080
	v_lshl_add_u64 v[206:207], v[210:211], 0, s[2:3]
	s_addc_u32 s31, s31, 0
	s_add_i32 s34, s58, s42
	global_load_lds_dwordx4 v[206:207], off
	v_lshl_add_u64 v[206:207], s[30:31], 0, v[208:209]
	s_mov_b32 m0, s34
	s_nop 0
	global_load_lds_dwordx4 v[206:207], off
	v_lshl_add_u64 v[206:207], s[30:31], 0, v[144:145]
	s_add_i32 m0, s34, 0x2000
	s_nop 0
	global_load_lds_dwordx4 v[206:207], off
	v_lshl_add_u64 v[206:207], v[212:213], 0, s[2:3]
	s_mov_b32 m0, s49
	s_nop 0
	global_load_lds_dwordx4 v[206:207], off
	v_lshl_add_u64 v[206:207], v[218:219], 0, s[2:3]
	s_mov_b32 m0, s50
	s_nop 0
	global_load_lds_dwordx4 v[206:207], off
	s_waitcnt vmcnt(8)
	s_waitcnt lgkmcnt(0)
	s_barrier
	s_setprio 1
	s_waitcnt lgkmcnt(0)
	v_mfma_f32_16x16x32_bf16 v[60:63], v[112:115], v[178:181], v[60:63]
	v_mfma_f32_16x16x32_bf16 v[56:59], v[120:123], v[178:181], v[56:59]
	v_mfma_f32_16x16x32_bf16 v[44:47], v[112:115], v[186:189], v[44:47]
	v_mfma_f32_16x16x32_bf16 v[40:43], v[120:123], v[186:189], v[40:43]
	v_mfma_f32_16x16x32_bf16 v[28:31], v[112:115], v[194:197], v[28:31]
	v_mfma_f32_16x16x32_bf16 v[24:27], v[120:123], v[194:197], v[24:27]
	v_mfma_f32_16x16x32_bf16 v[12:15], v[112:115], v[202:205], v[12:15]
	v_mfma_f32_16x16x32_bf16 v[8:11], v[120:123], v[202:205], v[8:11]
	v_mfma_f32_16x16x32_bf16 v[60:63], v[116:119], v[182:185], v[60:63]
	v_mfma_f32_16x16x32_bf16 v[56:59], v[124:127], v[182:185], v[56:59]
	v_mfma_f32_16x16x32_bf16 v[44:47], v[116:119], v[190:193], v[44:47]
	v_mfma_f32_16x16x32_bf16 v[40:43], v[124:127], v[190:193], v[40:43]
	v_mfma_f32_16x16x32_bf16 v[28:31], v[116:119], v[198:201], v[28:31]
	v_mfma_f32_16x16x32_bf16 v[24:27], v[124:127], v[198:201], v[24:27]
	v_mfma_f32_16x16x32_bf16 v[12:15], v[116:119], v[214:217], v[12:15]
	v_mfma_f32_16x16x32_bf16 v[8:11], v[124:127], v[214:217], v[8:11]
	s_setprio 0
	s_setprio 1
	v_mfma_f32_16x16x32_bf16 v[52:55], v[162:165], v[178:181], v[52:55]
	v_mfma_f32_16x16x32_bf16 v[48:51], v[170:173], v[178:181], v[48:51]
	v_mfma_f32_16x16x32_bf16 v[36:39], v[162:165], v[186:189], v[36:39]
	v_mfma_f32_16x16x32_bf16 v[32:35], v[170:173], v[186:189], v[32:35]
	v_mfma_f32_16x16x32_bf16 v[20:23], v[162:165], v[194:197], v[20:23]
	v_mfma_f32_16x16x32_bf16 v[16:19], v[170:173], v[194:197], v[16:19]
	v_mfma_f32_16x16x32_bf16 v[4:7], v[162:165], v[202:205], v[4:7]
	v_mfma_f32_16x16x32_bf16 v[0:3], v[170:173], v[202:205], v[0:3]
	v_mfma_f32_16x16x32_bf16 v[52:55], v[166:169], v[182:185], v[52:55]
	v_mfma_f32_16x16x32_bf16 v[48:51], v[174:177], v[182:185], v[48:51]
	v_mfma_f32_16x16x32_bf16 v[36:39], v[166:169], v[190:193], v[36:39]
	v_mfma_f32_16x16x32_bf16 v[32:35], v[174:177], v[190:193], v[32:35]
	v_mfma_f32_16x16x32_bf16 v[20:23], v[166:169], v[198:201], v[20:23]
	v_mfma_f32_16x16x32_bf16 v[16:19], v[174:177], v[198:201], v[16:19]
	v_mfma_f32_16x16x32_bf16 v[4:7], v[166:169], v[214:217], v[4:7]
	v_mfma_f32_16x16x32_bf16 v[0:3], v[174:177], v[214:217], v[0:3]
	s_setprio 0
	s_barrier
	s_add_i32 s56, s56, 2
	s_add_u32 s28, s28, 0x100
	s_addc_u32 s29, s29, 0
	s_add_u32 s54, s54, 0x100
	s_addc_u32 s55, s55, 0
	s_cmp_gt_u32 s56, 29
	s_cbranch_scc0 .LBB0_1479
	s_ashr_i32 s28, s24, 5
	s_ashr_i32 s29, s28, 31
	s_lshl_b64 s[28:29], s[28:29], 13
	s_cmpk_lt_i32 s24, 0x80
	s_cselect_b32 s29, s29, 0
	s_cselect_b32 s28, s28, 0x8000
	s_lshl_b64 s[28:29], s[28:29], 2
	v_lshl_or_b32 v174, s26, 8, v159
	s_add_u32 s28, s47, s28
	v_lshl_add_u32 v176, s24, 8, v155
	s_addc_u32 s29, s48, s29
	v_ashrrev_i32_e32 v175, 31, v174
	v_ashrrev_i32_e32 v177, 31, v176
	v_lshl_add_u64 v[116:117], v[174:175], 2, s[28:29]
	v_lshl_add_u64 v[178:179], v[176:177], 2, s[12:13]
	global_load_dwordx4 v[120:123], v[116:117], off offset:16
	global_load_dwordx4 v[124:127], v[116:117], off
	global_load_dwordx4 v[112:115], v[116:117], off offset:528
	s_nop 0
	global_load_dwordx4 v[116:119], v[116:117], off offset:512
	v_or_b32_e32 v172, 16, v176
	global_load_dword v180, v[178:179], off
	v_ashrrev_i32_e32 v173, 31, v172
	v_lshl_add_u64 v[162:163], v[172:173], 2, s[12:13]
	global_load_dword v170, v[162:163], off
	v_or_b32_e32 v168, 32, v176
	v_ashrrev_i32_e32 v169, 31, v168
	v_lshl_add_u64 v[162:163], v[168:169], 2, s[12:13]
	global_load_dword v166, v[162:163], off
	v_or_b32_e32 v164, 48, v176
	v_ashrrev_i32_e32 v165, 31, v164
	v_lshl_add_u64 v[162:163], v[164:165], 2, s[12:13]
	global_load_dword v162, v[162:163], off
	s_nop 0
	global_load_dword v160, v[178:179], off offset:512
	global_load_dword v158, v[178:179], off offset:576
	global_load_dword v156, v[178:179], off offset:640
	global_load_dword v154, v[178:179], off offset:704
	s_and_b64 vcc, exec, s[14:15]
	s_cbranch_vccz .LBB0_1482
	s_barrier
; __device__ __forceinline__ unsigned pk2(float lo, float hi) { const f32x2 v = {lo, hi}; return __builtin_bit_cast(unsigned, __builtin_convertvector(v, bf16x2_t)); }
; #define EPI_LOOP _Pragma("unroll") for (int ai = 0; ai < 2; ++ai) _Pragma("unroll") for (int m = 0; m < 4; ++m) _Pragma("unroll") for (int bj = 0; bj < 2; ++bj)
;     __device__ __forceinline__ void operator()(const f32x4 (&acc)[2][2][4][2], const Unit& un, int wr, int wc, int fr, int fq) const {
;     ...
;         EPI_LOOP { const int row = rbase + ai * 128 + m * 16, col = cw + bj * 128; const float r = rr[ai][m];
;             f32x4 v0 = acc[ai][bj][m][0] * r + s0[bj], v1 = acc[ai][bj][m][1] * r + s1[bj];
;             v0 = __builtin_elementwise_max(v0, (f32x4){0.f, 0.f, 0.f, 0.f}); v1 = __builtin_elementwise_max(v1, (f32x4){0.f, 0.f, 0.f, 0.f}); v0 = v0 * v0; v1 = v1 * v1;
;             u32x4 w; w.x = pk2(v0.x, v0.y); w.y = pk2(v0.z, v0.w); w.z = pk2(v1.x, v1.y); w.w = pk2(v1.z, v1.w);
;             *(u32x4*)(o + (size_t)row * DFF + col) = w; }
.LBB0_1482:
	v_lshlrev_b64 v[176:177], 14, v[176:177]
	s_mov_b64 s[24:25], 0x200000
	v_readlane_b32 s58, v254, 51
	s_waitcnt vmcnt(0)
	v_pk_fma_f32 v[142:143], v[142:143], v[180:181], v[126:127] op_sel_hi:[1,0,1]
	v_pk_fma_f32 v[140:141], v[140:141], v[180:181], v[124:125] op_sel_hi:[1,0,1]
	v_pk_fma_f32 v[138:139], v[138:139], v[180:181], v[122:123] op_sel_hi:[1,0,1]
	v_pk_fma_f32 v[136:137], v[136:137], v[180:181], v[120:121] op_sel_hi:[1,0,1]
	v_max_f32_e32 v143, 0, v143
	v_max_f32_e32 v142, 0, v142
	v_max_f32_e32 v141, 0, v141
	v_max_f32_e32 v140, 0, v140
	v_max_f32_e32 v139, 0, v139
	v_max_f32_e32 v138, 0, v138
	v_max_f32_e32 v137, 0, v137
	v_max_f32_e32 v136, 0, v136
	v_pk_mul_f32 v[142:143], v[142:143], v[142:143]
	v_pk_mul_f32 v[140:141], v[140:141], v[140:141]
	v_pk_mul_f32 v[138:139], v[138:139], v[138:139]
	v_pk_mul_f32 v[136:137], v[136:137], v[136:137]
	v_cvt_pk_bf16_f32 v140, v140, v141
	v_cvt_pk_bf16_f32 v141, v142, v143
	v_cvt_pk_bf16_f32 v142, v136, v137
	v_cvt_pk_bf16_f32 v143, v138, v139
	v_lshl_add_u64 v[136:137], s[10:11], 0, v[176:177]
	v_lshlrev_b64 v[138:139], 1, v[174:175]
	v_pk_fma_f32 v[134:135], v[134:135], v[180:181], v[118:119] op_sel_hi:[1,0,1]
	v_pk_fma_f32 v[132:133], v[132:133], v[180:181], v[116:117] op_sel_hi:[1,0,1]
	v_pk_fma_f32 v[130:131], v[130:131], v[180:181], v[114:115] op_sel_hi:[1,0,1]
	v_pk_fma_f32 v[128:129], v[128:129], v[180:181], v[112:113] op_sel_hi:[1,0,1]
	v_lshl_add_u64 v[136:137], v[136:137], 0, v[138:139]
	v_max_f32_e32 v135, 0, v135
	v_max_f32_e32 v134, 0, v134
	v_max_f32_e32 v133, 0, v133
	v_max_f32_e32 v132, 0, v132
	v_max_f32_e32 v131, 0, v131
	v_max_f32_e32 v130, 0, v130
	v_max_f32_e32 v129, 0, v129
	v_max_f32_e32 v128, 0, v128
	global_store_dwordx4 v[136:137], v[140:143], off
	v_pk_mul_f32 v[134:135], v[134:135], v[134:135]
	v_pk_mul_f32 v[132:133], v[132:133], v[132:133]
	v_pk_mul_f32 v[140:141], v[130:131], v[130:131]
	v_pk_mul_f32 v[130:131], v[128:129], v[128:129]
	v_pk_fma_f32 v[108:109], v[108:109], v[170:171], v[124:125] op_sel_hi:[1,0,1]
	v_cvt_pk_bf16_f32 v128, v132, v133
	v_cvt_pk_bf16_f32 v129, v134, v135
	v_cvt_pk_bf16_f32 v130, v130, v131
	v_cvt_pk_bf16_f32 v131, v140, v141
	v_pk_fma_f32 v[110:111], v[110:111], v[170:171], v[126:127] op_sel_hi:[1,0,1]
	v_pk_fma_f32 v[106:107], v[106:107], v[170:171], v[122:123] op_sel_hi:[1,0,1]
	v_pk_fma_f32 v[104:105], v[104:105], v[170:171], v[120:121] op_sel_hi:[1,0,1]
	v_max_f32_e32 v109, 0, v109
	v_max_f32_e32 v108, 0, v108
	global_store_dwordx4 v[136:137], v[128:131], off offset:256
	v_max_f32_e32 v111, 0, v111
	v_max_f32_e32 v110, 0, v110
	v_lshlrev_b64 v[128:129], 14, v[172:173]
	v_max_f32_e32 v107, 0, v107
	v_max_f32_e32 v106, 0, v106
	v_max_f32_e32 v105, 0, v105
	v_max_f32_e32 v104, 0, v104
	v_pk_mul_f32 v[108:109], v[108:109], v[108:109]
	v_pk_mul_f32 v[110:111], v[110:111], v[110:111]
	v_pk_mul_f32 v[130:131], v[106:107], v[106:107]
	v_pk_mul_f32 v[106:107], v[104:105], v[104:105]
	v_cvt_pk_bf16_f32 v104, v108, v109
	v_lshl_add_u64 v[108:109], s[10:11], 0, v[128:129]
	v_pk_fma_f32 v[102:103], v[102:103], v[170:171], v[118:119] op_sel_hi:[1,0,1]
	v_pk_fma_f32 v[100:101], v[100:101], v[170:171], v[116:117] op_sel_hi:[1,0,1]
	v_pk_fma_f32 v[98:99], v[98:99], v[170:171], v[114:115] op_sel_hi:[1,0,1]
	v_pk_fma_f32 v[96:97], v[96:97], v[170:171], v[112:113] op_sel_hi:[1,0,1]
	v_cvt_pk_bf16_f32 v105, v110, v111
	v_cvt_pk_bf16_f32 v106, v106, v107
	v_cvt_pk_bf16_f32 v107, v130, v131
	v_lshl_add_u64 v[108:109], v[108:109], 0, v[138:139]
	v_max_f32_e32 v103, 0, v103
	v_max_f32_e32 v102, 0, v102
	v_max_f32_e32 v101, 0, v101
	v_max_f32_e32 v100, 0, v100
	v_max_f32_e32 v99, 0, v99
	v_max_f32_e32 v98, 0, v98
	v_max_f32_e32 v97, 0, v97
	v_max_f32_e32 v96, 0, v96
	global_store_dwordx4 v[108:109], v[104:107], off
	v_pk_mul_f32 v[102:103], v[102:103], v[102:103]
	v_pk_mul_f32 v[100:101], v[100:101], v[100:101]
	v_pk_mul_f32 v[104:105], v[98:99], v[98:99]
	v_pk_mul_f32 v[98:99], v[96:97], v[96:97]
	v_pk_fma_f32 v[92:93], v[92:93], v[166:167], v[124:125] op_sel_hi:[1,0,1]
	v_cvt_pk_bf16_f32 v96, v100, v101
	v_cvt_pk_bf16_f32 v97, v102, v103
	v_cvt_pk_bf16_f32 v98, v98, v99
	v_cvt_pk_bf16_f32 v99, v104, v105
	v_pk_fma_f32 v[94:95], v[94:95], v[166:167], v[126:127] op_sel_hi:[1,0,1]
	v_pk_fma_f32 v[90:91], v[90:91], v[166:167], v[122:123] op_sel_hi:[1,0,1]
	v_pk_fma_f32 v[88:89], v[88:89], v[166:167], v[120:121] op_sel_hi:[1,0,1]
	v_max_f32_e32 v93, 0, v93
	v_max_f32_e32 v92, 0, v92
	global_store_dwordx4 v[108:109], v[96:99], off offset:256
	v_max_f32_e32 v95, 0, v95
	v_max_f32_e32 v94, 0, v94
	v_lshlrev_b64 v[96:97], 14, v[168:169]
	v_max_f32_e32 v91, 0, v91
	v_max_f32_e32 v90, 0, v90
	v_max_f32_e32 v89, 0, v89
	v_max_f32_e32 v88, 0, v88
	v_pk_mul_f32 v[92:93], v[92:93], v[92:93]
	v_pk_mul_f32 v[94:95], v[94:95], v[94:95]
	v_pk_mul_f32 v[98:99], v[90:91], v[90:91]
	v_pk_mul_f32 v[90:91], v[88:89], v[88:89]
	v_cvt_pk_bf16_f32 v88, v92, v93
	v_lshl_add_u64 v[92:93], s[10:11], 0, v[96:97]
	v_pk_fma_f32 v[86:87], v[86:87], v[166:167], v[118:119] op_sel_hi:[1,0,1]
	v_pk_fma_f32 v[84:85], v[84:85], v[166:167], v[116:117] op_sel_hi:[1,0,1]
	v_pk_fma_f32 v[82:83], v[82:83], v[166:167], v[114:115] op_sel_hi:[1,0,1]
	v_pk_fma_f32 v[80:81], v[80:81], v[166:167], v[112:113] op_sel_hi:[1,0,1]
	v_cvt_pk_bf16_f32 v89, v94, v95
	v_cvt_pk_bf16_f32 v90, v90, v91
	v_cvt_pk_bf16_f32 v91, v98, v99
	v_lshl_add_u64 v[92:93], v[92:93], 0, v[138:139]
	v_max_f32_e32 v87, 0, v87
	v_max_f32_e32 v86, 0, v86
	v_max_f32_e32 v85, 0, v85
	v_max_f32_e32 v84, 0, v84
	v_max_f32_e32 v83, 0, v83
	v_max_f32_e32 v82, 0, v82
	v_max_f32_e32 v81, 0, v81
	v_max_f32_e32 v80, 0, v80
; __device__ __forceinline__ unsigned pk2(float lo, float hi) { const f32x2 v = {lo, hi}; return __builtin_bit_cast(unsigned, __builtin_convertvector(v, bf16x2_t)); }
; #define EPI_LOOP _Pragma("unroll") for (int ai = 0; ai < 2; ++ai) _Pragma("unroll") for (int m = 0; m < 4; ++m) _Pragma("unroll") for (int bj = 0; bj < 2; ++bj)
;     __device__ __forceinline__ void operator()(const f32x4 (&acc)[2][2][4][2], const Unit& un, int wr, int wc, int fr, int fq) const {
;     ...
;         EPI_LOOP { const int row = rbase + ai * 128 + m * 16, col = cw + bj * 128; const float r = rr[ai][m];
;             f32x4 v0 = acc[ai][bj][m][0] * r + s0[bj], v1 = acc[ai][bj][m][1] * r + s1[bj];
;             v0 = __builtin_elementwise_max(v0, (f32x4){0.f, 0.f, 0.f, 0.f}); v1 = __builtin_elementwise_max(v1, (f32x4){0.f, 0.f, 0.f, 0.f}); v0 = v0 * v0; v1 = v1 * v1;
;             u32x4 w; w.x = pk2(v0.x, v0.y); w.y = pk2(v0.z, v0.w); w.z = pk2(v1.x, v1.y); w.w = pk2(v1.z, v1.w);
;             *(u32x4*)(o + (size_t)row * DFF + col) = w; }
	global_store_dwordx4 v[92:93], v[88:91], off
	v_pk_mul_f32 v[86:87], v[86:87], v[86:87]
	v_pk_mul_f32 v[84:85], v[84:85], v[84:85]
	v_pk_mul_f32 v[88:89], v[82:83], v[82:83]
	v_pk_mul_f32 v[82:83], v[80:81], v[80:81]
	v_pk_fma_f32 v[76:77], v[76:77], v[162:163], v[124:125] op_sel_hi:[1,0,1]
	v_cvt_pk_bf16_f32 v80, v84, v85
	v_cvt_pk_bf16_f32 v81, v86, v87
	v_cvt_pk_bf16_f32 v82, v82, v83
	v_cvt_pk_bf16_f32 v83, v88, v89
	v_pk_fma_f32 v[78:79], v[78:79], v[162:163], v[126:127] op_sel_hi:[1,0,1]
	v_pk_fma_f32 v[74:75], v[74:75], v[162:163], v[122:123] op_sel_hi:[1,0,1]
	v_pk_fma_f32 v[72:73], v[72:73], v[162:163], v[120:121] op_sel_hi:[1,0,1]
	v_max_f32_e32 v77, 0, v77
	v_max_f32_e32 v76, 0, v76
	global_store_dwordx4 v[92:93], v[80:83], off offset:256
	v_max_f32_e32 v79, 0, v79
	v_max_f32_e32 v78, 0, v78
	v_lshlrev_b64 v[80:81], 14, v[164:165]
	v_max_f32_e32 v75, 0, v75
	v_max_f32_e32 v74, 0, v74
	v_max_f32_e32 v73, 0, v73
	v_max_f32_e32 v72, 0, v72
	v_pk_mul_f32 v[76:77], v[76:77], v[76:77]
	v_pk_mul_f32 v[78:79], v[78:79], v[78:79]
	v_pk_mul_f32 v[82:83], v[74:75], v[74:75]
	v_pk_mul_f32 v[74:75], v[72:73], v[72:73]
	v_cvt_pk_bf16_f32 v72, v76, v77
	v_lshl_add_u64 v[76:77], s[10:11], 0, v[80:81]
	v_pk_fma_f32 v[70:71], v[70:71], v[162:163], v[118:119] op_sel_hi:[1,0,1]
	v_pk_fma_f32 v[68:69], v[68:69], v[162:163], v[116:117] op_sel_hi:[1,0,1]
	v_pk_fma_f32 v[66:67], v[66:67], v[162:163], v[114:115] op_sel_hi:[1,0,1]
	v_pk_fma_f32 v[64:65], v[64:65], v[162:163], v[112:113] op_sel_hi:[1,0,1]
	v_cvt_pk_bf16_f32 v73, v78, v79
	v_cvt_pk_bf16_f32 v74, v74, v75
	v_cvt_pk_bf16_f32 v75, v82, v83
	v_lshl_add_u64 v[76:77], v[76:77], 0, v[138:139]
	v_max_f32_e32 v71, 0, v71
	v_max_f32_e32 v70, 0, v70
	v_max_f32_e32 v69, 0, v69
	v_max_f32_e32 v68, 0, v68
	v_max_f32_e32 v67, 0, v67
	v_max_f32_e32 v66, 0, v66
	v_max_f32_e32 v65, 0, v65
	v_max_f32_e32 v64, 0, v64
	v_pk_fma_f32 v[62:63], v[62:63], v[160:161], v[126:127] op_sel_hi:[1,0,1]
	global_store_dwordx4 v[76:77], v[72:75], off
	v_pk_mul_f32 v[70:71], v[70:71], v[70:71]
	v_pk_mul_f32 v[68:69], v[68:69], v[68:69]
	v_pk_mul_f32 v[72:73], v[66:67], v[66:67]
	v_pk_mul_f32 v[66:67], v[64:65], v[64:65]
	v_pk_fma_f32 v[60:61], v[60:61], v[160:161], v[124:125] op_sel_hi:[1,0,1]
	v_pk_fma_f32 v[58:59], v[58:59], v[160:161], v[122:123] op_sel_hi:[1,0,1]
	v_pk_fma_f32 v[56:57], v[56:57], v[160:161], v[120:121] op_sel_hi:[1,0,1]
	v_max_f32_e32 v63, 0, v63
	v_max_f32_e32 v62, 0, v62
	v_cvt_pk_bf16_f32 v64, v68, v69
	v_cvt_pk_bf16_f32 v65, v70, v71
	v_cvt_pk_bf16_f32 v66, v66, v67
	v_cvt_pk_bf16_f32 v67, v72, v73
	v_max_f32_e32 v61, 0, v61
	v_max_f32_e32 v60, 0, v60
	v_max_f32_e32 v59, 0, v59
	v_max_f32_e32 v58, 0, v58
	v_max_f32_e32 v57, 0, v57
	v_max_f32_e32 v56, 0, v56
	v_pk_mul_f32 v[62:63], v[62:63], v[62:63]
	global_store_dwordx4 v[76:77], v[64:67], off offset:256
	v_pk_mul_f32 v[60:61], v[60:61], v[60:61]
	v_pk_fma_f32 v[54:55], v[54:55], v[160:161], v[118:119] op_sel_hi:[1,0,1]
	v_pk_mul_f32 v[64:65], v[58:59], v[58:59]
	v_pk_mul_f32 v[58:59], v[56:57], v[56:57]
	v_cvt_pk_bf16_f32 v57, v62, v63
	v_add_co_u32_e32 v62, vcc, s78, v136
	v_pk_fma_f32 v[52:53], v[52:53], v[160:161], v[116:117] op_sel_hi:[1,0,1]
	v_pk_fma_f32 v[50:51], v[50:51], v[160:161], v[114:115] op_sel_hi:[1,0,1]
	v_pk_fma_f32 v[48:49], v[48:49], v[160:161], v[112:113] op_sel_hi:[1,0,1]
	v_cvt_pk_bf16_f32 v56, v60, v61
	v_cvt_pk_bf16_f32 v58, v58, v59
	v_cvt_pk_bf16_f32 v59, v64, v65
	v_addc_co_u32_e32 v63, vcc, 0, v137, vcc
	v_max_f32_e32 v55, 0, v55
	v_max_f32_e32 v54, 0, v54
	v_max_f32_e32 v53, 0, v53
	v_max_f32_e32 v52, 0, v52
	v_max_f32_e32 v51, 0, v51
	v_max_f32_e32 v50, 0, v50
	v_max_f32_e32 v49, 0, v49
	v_max_f32_e32 v48, 0, v48
	v_pk_fma_f32 v[46:47], v[46:47], v[158:159], v[126:127] op_sel_hi:[1,0,1]
	global_store_dwordx4 v[62:63], v[56:59], off
	v_pk_mul_f32 v[54:55], v[54:55], v[54:55]
	v_pk_mul_f32 v[52:53], v[52:53], v[52:53]
	v_pk_mul_f32 v[56:57], v[50:51], v[50:51]
	v_pk_mul_f32 v[50:51], v[48:49], v[48:49]
	v_pk_fma_f32 v[44:45], v[44:45], v[158:159], v[124:125] op_sel_hi:[1,0,1]
	v_pk_fma_f32 v[42:43], v[42:43], v[158:159], v[122:123] op_sel_hi:[1,0,1]
	v_pk_fma_f32 v[40:41], v[40:41], v[158:159], v[120:121] op_sel_hi:[1,0,1]
	v_max_f32_e32 v47, 0, v47
	v_max_f32_e32 v46, 0, v46
	v_lshl_add_u64 v[60:61], v[136:137], 0, s[24:25]
	v_cvt_pk_bf16_f32 v48, v52, v53
	v_cvt_pk_bf16_f32 v49, v54, v55
	v_cvt_pk_bf16_f32 v50, v50, v51
	v_cvt_pk_bf16_f32 v51, v56, v57
	v_max_f32_e32 v45, 0, v45
	v_max_f32_e32 v44, 0, v44
	v_max_f32_e32 v43, 0, v43
	v_max_f32_e32 v42, 0, v42
	v_max_f32_e32 v41, 0, v41
	v_max_f32_e32 v40, 0, v40
	v_pk_mul_f32 v[46:47], v[46:47], v[46:47]
	global_store_dwordx4 v[60:61], v[48:51], off offset:256
	v_pk_mul_f32 v[44:45], v[44:45], v[44:45]
	v_pk_fma_f32 v[38:39], v[38:39], v[158:159], v[118:119] op_sel_hi:[1,0,1]
	v_pk_mul_f32 v[48:49], v[42:43], v[42:43]
	v_pk_mul_f32 v[42:43], v[40:41], v[40:41]
	v_cvt_pk_bf16_f32 v41, v46, v47
	v_add_co_u32_e32 v46, vcc, s74, v136
; #define PG8_BAR __builtin_amdgcn_s_barrier()
; __device__ __forceinline__ unsigned pk2(float lo, float hi) { const f32x2 v = {lo, hi}; return __builtin_bit_cast(unsigned, __builtin_convertvector(v, bf16x2_t)); }
; #define EPI_LOOP _Pragma("unroll") for (int ai = 0; ai < 2; ++ai) _Pragma("unroll") for (int m = 0; m < 4; ++m) _Pragma("unroll") for (int bj = 0; bj < 2; ++bj)
; template <class Epi, class Sched, bool ALIGN_EPI = false, bool SP2 = false>
; __device__ __forceinline__ void gemm_phase(PG8_LAS unsigned char* lds, const Gemm g, const Sched& S, const Epi& E, const int tid) {
;     ...
;         if constexpr (!Epi::AFTER_DRAIN) { E(acc, cur, wr, wc, fr, fq); S.done(cur); }
;         if (!has_next) break;
; #pragma unroll
;         for (int a = 0; a < 2; ++a)
; #pragma unroll
;             for (int b = 0; b < 2; ++b)
; #pragma unroll
;                 for (int m = 0; m < 4; ++m)
; #pragma unroll
;                     for (int n = 0; n < 2; ++n) acc[a][b][m][n] = (f32x4){0.f, 0.f, 0.f, 0.f};
;         cur = nxt; cA = nA; cB = nB; ++ui;
;         if constexpr (ALIGN_EPI) { if (wr == 1) PG8_BAR; }
;     }
;     __device__ __forceinline__ void operator()(const f32x4 (&acc)[2][2][4][2], const Unit& un, int wr, int wc, int fr, int fq) const {
;     ...
;         EPI_LOOP { const int row = rbase + ai * 128 + m * 16, col = cw + bj * 128; const float r = rr[ai][m];
;             f32x4 v0 = acc[ai][bj][m][0] * r + s0[bj], v1 = acc[ai][bj][m][1] * r + s1[bj];
;             v0 = __builtin_elementwise_max(v0, (f32x4){0.f, 0.f, 0.f, 0.f}); v1 = __builtin_elementwise_max(v1, (f32x4){0.f, 0.f, 0.f, 0.f}); v0 = v0 * v0; v1 = v1 * v1;
;             u32x4 w; w.x = pk2(v0.x, v0.y); w.y = pk2(v0.z, v0.w); w.z = pk2(v1.x, v1.y); w.w = pk2(v1.z, v1.w);
;             *(u32x4*)(o + (size_t)row * DFF + col) = w; }
	v_pk_fma_f32 v[36:37], v[36:37], v[158:159], v[116:117] op_sel_hi:[1,0,1]
	v_pk_fma_f32 v[34:35], v[34:35], v[158:159], v[114:115] op_sel_hi:[1,0,1]
	v_pk_fma_f32 v[32:33], v[32:33], v[158:159], v[112:113] op_sel_hi:[1,0,1]
	v_cvt_pk_bf16_f32 v40, v44, v45
	v_cvt_pk_bf16_f32 v42, v42, v43
	v_cvt_pk_bf16_f32 v43, v48, v49
	v_addc_co_u32_e32 v47, vcc, 0, v137, vcc
	v_max_f32_e32 v39, 0, v39
	v_max_f32_e32 v38, 0, v38
	v_max_f32_e32 v37, 0, v37
	v_max_f32_e32 v36, 0, v36
	v_max_f32_e32 v35, 0, v35
	v_max_f32_e32 v34, 0, v34
	v_max_f32_e32 v33, 0, v33
	v_max_f32_e32 v32, 0, v32
	v_pk_fma_f32 v[30:31], v[30:31], v[156:157], v[126:127] op_sel_hi:[1,0,1]
	s_mov_b64 s[24:25], 0x240000
	global_store_dwordx4 v[46:47], v[40:43], off
	v_pk_mul_f32 v[38:39], v[38:39], v[38:39]
	v_pk_mul_f32 v[36:37], v[36:37], v[36:37]
	v_pk_mul_f32 v[40:41], v[34:35], v[34:35]
	v_pk_mul_f32 v[34:35], v[32:33], v[32:33]
	v_pk_fma_f32 v[28:29], v[28:29], v[156:157], v[124:125] op_sel_hi:[1,0,1]
	v_pk_fma_f32 v[26:27], v[26:27], v[156:157], v[122:123] op_sel_hi:[1,0,1]
	v_pk_fma_f32 v[24:25], v[24:25], v[156:157], v[120:121] op_sel_hi:[1,0,1]
	v_max_f32_e32 v31, 0, v31
	v_max_f32_e32 v30, 0, v30
	v_lshl_add_u64 v[44:45], v[136:137], 0, s[24:25]
	v_cvt_pk_bf16_f32 v32, v36, v37
	v_cvt_pk_bf16_f32 v33, v38, v39
	v_cvt_pk_bf16_f32 v34, v34, v35
	v_cvt_pk_bf16_f32 v35, v40, v41
	v_max_f32_e32 v29, 0, v29
	v_max_f32_e32 v28, 0, v28
	v_max_f32_e32 v27, 0, v27
	v_max_f32_e32 v26, 0, v26
	v_max_f32_e32 v25, 0, v25
	v_max_f32_e32 v24, 0, v24
	v_pk_mul_f32 v[30:31], v[30:31], v[30:31]
	global_store_dwordx4 v[44:45], v[32:35], off offset:256
	v_pk_mul_f32 v[28:29], v[28:29], v[28:29]
	v_pk_fma_f32 v[22:23], v[22:23], v[156:157], v[118:119] op_sel_hi:[1,0,1]
	v_pk_mul_f32 v[32:33], v[26:27], v[26:27]
	v_pk_mul_f32 v[26:27], v[24:25], v[24:25]
	v_cvt_pk_bf16_f32 v25, v30, v31
	v_add_co_u32_e32 v30, vcc, s71, v136
	v_pk_fma_f32 v[20:21], v[20:21], v[156:157], v[116:117] op_sel_hi:[1,0,1]
	v_pk_fma_f32 v[18:19], v[18:19], v[156:157], v[114:115] op_sel_hi:[1,0,1]
	v_pk_fma_f32 v[16:17], v[16:17], v[156:157], v[112:113] op_sel_hi:[1,0,1]
	v_cvt_pk_bf16_f32 v24, v28, v29
	v_cvt_pk_bf16_f32 v26, v26, v27
	v_cvt_pk_bf16_f32 v27, v32, v33
	v_addc_co_u32_e32 v31, vcc, 0, v137, vcc
	v_max_f32_e32 v23, 0, v23
	v_max_f32_e32 v22, 0, v22
	v_max_f32_e32 v21, 0, v21
	v_max_f32_e32 v20, 0, v20
	v_max_f32_e32 v19, 0, v19
	v_max_f32_e32 v18, 0, v18
	v_max_f32_e32 v17, 0, v17
	v_max_f32_e32 v16, 0, v16
	v_pk_fma_f32 v[14:15], v[14:15], v[154:155], v[126:127] op_sel_hi:[1,0,1]
	s_mov_b64 s[24:25], 0x280000
	global_store_dwordx4 v[30:31], v[24:27], off
	v_pk_mul_f32 v[22:23], v[22:23], v[22:23]
	v_pk_mul_f32 v[20:21], v[20:21], v[20:21]
	v_pk_mul_f32 v[24:25], v[18:19], v[18:19]
	v_pk_mul_f32 v[18:19], v[16:17], v[16:17]
	v_pk_fma_f32 v[12:13], v[12:13], v[154:155], v[124:125] op_sel_hi:[1,0,1]
	v_pk_fma_f32 v[10:11], v[10:11], v[154:155], v[122:123] op_sel_hi:[1,0,1]
	v_pk_fma_f32 v[8:9], v[8:9], v[154:155], v[120:121] op_sel_hi:[1,0,1]
	v_max_f32_e32 v15, 0, v15
	v_max_f32_e32 v14, 0, v14
	v_lshl_add_u64 v[28:29], v[136:137], 0, s[24:25]
	v_cvt_pk_bf16_f32 v16, v20, v21
	v_cvt_pk_bf16_f32 v17, v22, v23
	v_cvt_pk_bf16_f32 v18, v18, v19
	v_cvt_pk_bf16_f32 v19, v24, v25
	v_max_f32_e32 v13, 0, v13
	v_max_f32_e32 v12, 0, v12
	v_max_f32_e32 v11, 0, v11
	v_max_f32_e32 v10, 0, v10
	v_max_f32_e32 v9, 0, v9
	v_max_f32_e32 v8, 0, v8
	v_pk_mul_f32 v[14:15], v[14:15], v[14:15]
	global_store_dwordx4 v[28:29], v[16:19], off offset:256
	v_pk_mul_f32 v[12:13], v[12:13], v[12:13]
	v_pk_fma_f32 v[6:7], v[6:7], v[154:155], v[118:119] op_sel_hi:[1,0,1]
	v_pk_mul_f32 v[16:17], v[10:11], v[10:11]
	v_pk_mul_f32 v[10:11], v[8:9], v[8:9]
	v_cvt_pk_bf16_f32 v9, v14, v15
	v_add_co_u32_e32 v14, vcc, s72, v136
	v_pk_fma_f32 v[4:5], v[4:5], v[154:155], v[116:117] op_sel_hi:[1,0,1]
	v_pk_fma_f32 v[2:3], v[2:3], v[154:155], v[114:115] op_sel_hi:[1,0,1]
	v_pk_fma_f32 v[0:1], v[0:1], v[154:155], v[112:113] op_sel_hi:[1,0,1]
	v_cvt_pk_bf16_f32 v8, v12, v13
	v_cvt_pk_bf16_f32 v10, v10, v11
	v_cvt_pk_bf16_f32 v11, v16, v17
	v_addc_co_u32_e32 v15, vcc, 0, v137, vcc
	v_max_f32_e32 v7, 0, v7
	v_max_f32_e32 v6, 0, v6
	v_max_f32_e32 v5, 0, v5
	v_max_f32_e32 v4, 0, v4
	v_max_f32_e32 v3, 0, v3
	v_max_f32_e32 v2, 0, v2
	v_max_f32_e32 v1, 0, v1
	v_max_f32_e32 v0, 0, v0
	s_mov_b64 s[24:25], 0x2c0000
	global_store_dwordx4 v[14:15], v[8:11], off
	v_pk_mul_f32 v[6:7], v[6:7], v[6:7]
	v_pk_mul_f32 v[4:5], v[4:5], v[4:5]
	v_pk_mul_f32 v[8:9], v[2:3], v[2:3]
	v_pk_mul_f32 v[2:3], v[0:1], v[0:1]
	v_lshl_add_u64 v[12:13], v[136:137], 0, s[24:25]
	v_cvt_pk_bf16_f32 v0, v4, v5
	v_cvt_pk_bf16_f32 v1, v6, v7
	v_cvt_pk_bf16_f32 v2, v2, v3
	v_cvt_pk_bf16_f32 v3, v8, v9
	s_mov_b64 s[24:25], -1
	s_andn2_b64 vcc, exec, s[0:1]
	global_store_dwordx4 v[12:13], v[0:3], off offset:256
	s_cbranch_vccnz .LBB0_1475
	s_andn2_b64 vcc, exec, s[6:7]
	s_cbranch_vccnz .LBB0_1474
	s_barrier
	s_branch .LBB0_1474
